# snake MFMA order in the regular GEMM blocks (adjacent MFMAs share accumulator or an operand register; k-half order flipped on every second accumulator) on top of chains + P16 warm-up
# speedup vs baseline: 1.0168x; 1.0168x over previous
; #define PG8_STAGE(bufoff, gbase, voff) do { if constexpr (ABL & 1) break; glds16s<(bufoff)>((voff)[0], (const void*)(gbase), ldsbw); glds16s<(bufoff) + 8192>((voff)[1], (const void*)(gbase), ldsbw); } while (0)
; #define PG8_LDA(dst, b, h) do { if constexpr (ABL & 4) break; _Pragma("unroll") for (int m = 0; m < 4; ++m) _Pragma("unroll") for (int k = 0; k < 2; ++k) dst[m][k] = *(const LAS f16x8*)(lds + PG8_SA(b, h) + aoff + m * 2048 + k * 1024); } while (0)
; #define PG8_LDB(dst, b, h) do { if constexpr (ABL & 4) break; _Pragma("unroll") for (int n = 0; n < 2; ++n) _Pragma("unroll") for (int k = 0; k < 2; ++k) dst[n][k] = *(const LAS f16x8*)(lds + PG8_SB(b, h) + boff + n * 2048 + k * 1024); } while (0)
; #define PG8_BAR __builtin_amdgcn_s_barrier()
;     ...
;         for (int t = 0; t < nt; t += 2) {
;             const bool last = (t == nt - 2);
;             const char* a1 = cA + (size_t)(t + 1) * kstep;
;             const char* a2 = last ? nA : cA + (size_t)(t + 2) * kstep; const char* b2 = last ? nB : cB + (size_t)(t + 2) * kstep;
;             const char* a3 = a2 + kstep; const char* b3 = b2 + kstep;
;             if (last && has_next) S.a_ready(nxt);
;             if constexpr (SP2) {
;             PG8_LDB(B0, 0, 0); PG8_LDB(B1, 0, 1); PG8_SCHED; PG8_LDA(At, 0, 0); PG8_STAGE(PG8_SA(1, 1), a1 + hstep, voffA);
;             PG8_WAIT_V(8); PG8_WAIT_L(0); PG8_BAR; PG8_MMAF(0, 0, At, B0); PG8_MMAF(0, 1, At, B1); PG8_BAR; PG8_SCHED;
;             const bool fin = last && !has_next;
;             PG8_LDA(At, 0, 1); if (!fin) { PG8_STAGE(PG8_SB(0, 0), b2, voffB); PG8_STAGE(PG8_SB(0, 1), b2 + hstep, voffB); PG8_STAGE(PG8_SA(0, 0), a2, voffA); }
;             if (!fin) PG8_WAIT_V(8); else PG8_WAIT_V(2); PG8_WAIT_L(0); PG8_BAR; PG8_MMAF(1, 0, At, B0); PG8_MMAF(1, 1, At, B1); PG8_BAR; PG8_SCHED;
;             PG8_LDB(B0, 1, 0); PG8_LDB(B1, 1, 1); PG8_SCHED; PG8_LDA(At, 1, 0); if (!fin) PG8_STAGE(PG8_SA(0, 1), a2 + hstep, voffA);
;             if (!fin) PG8_WAIT_V(8); else PG8_WAIT_V(0); PG8_WAIT_L(0); PG8_BAR; PG8_MMA(0, 0, At, B0); PG8_MMA(0, 1, At, B1); PG8_BAR; PG8_SCHED;
;             PG8_LDA(At, 1, 1); if (!fin) { PG8_STAGE(PG8_SB(1, 0), b3, voffB); PG8_STAGE(PG8_SB(1, 1), b3 + hstep, voffB); PG8_STAGE(PG8_SA(1, 0), a3, voffA); }
;             if (!fin) PG8_WAIT_V(8); PG8_WAIT_L(0); PG8_BAR; PG8_MMA(1, 0, At, B0); PG8_MMA(1, 1, At, B1); PG8_BAR; PG8_SCHED;
.LBB0_230:
	s_waitcnt lgkmcnt(0)
	s_barrier
	v_mfma_f32_16x16x32_f16 v[54:57], v[154:157], v[186:189], v[54:57]
	s_setprio 1
	v_mfma_f32_16x16x32_f16 v[54:57], v[158:161], v[190:193], v[54:57]
	v_mfma_f32_16x16x32_f16 v[46:49], v[150:153], v[190:193], v[46:49]
	v_mfma_f32_16x16x32_f16 v[46:49], v[146:149], v[186:189], v[46:49]
	v_mfma_f32_16x16x32_f16 v[30:33], v[146:149], v[178:181], v[30:33]
	v_mfma_f32_16x16x32_f16 v[30:33], v[150:153], v[182:185], v[30:33]
	v_mfma_f32_16x16x32_f16 v[34:37], v[158:161], v[182:185], v[34:37]
	v_mfma_f32_16x16x32_f16 v[34:37], v[154:157], v[178:181], v[34:37]
	v_mfma_f32_16x16x32_f16 v[18:21], v[154:157], v[170:173], v[18:21]
	v_mfma_f32_16x16x32_f16 v[18:21], v[158:161], v[174:177], v[18:21]
	v_mfma_f32_16x16x32_f16 v[14:17], v[150:153], v[174:177], v[14:17]
	v_mfma_f32_16x16x32_f16 v[14:17], v[146:149], v[170:173], v[14:17]
	v_mfma_f32_16x16x32_f16 v[2:5], v[146:149], v[162:165], v[2:5]
	v_mfma_f32_16x16x32_f16 v[2:5], v[150:153], v[166:169], v[2:5]
	v_mfma_f32_16x16x32_f16 v[6:9], v[158:161], v[166:169], v[6:9]
	v_mfma_f32_16x16x32_f16 v[6:9], v[154:157], v[162:165], v[6:9]
	v_mfma_f32_16x16x32_f16 v[82:85], v[138:141], v[186:189], v[82:85]
	v_mfma_f32_16x16x32_f16 v[82:85], v[142:145], v[190:193], v[82:85]
	v_mfma_f32_16x16x32_f16 v[70:73], v[134:137], v[190:193], v[70:73]
	v_mfma_f32_16x16x32_f16 v[70:73], v[130:133], v[186:189], v[70:73]
	v_mfma_f32_16x16x32_f16 v[42:45], v[130:133], v[178:181], v[42:45]
	v_mfma_f32_16x16x32_f16 v[42:45], v[134:137], v[182:185], v[42:45]
	v_mfma_f32_16x16x32_f16 v[62:65], v[142:145], v[182:185], v[62:65]
	v_mfma_f32_16x16x32_f16 v[62:65], v[138:141], v[178:181], v[62:65]
	v_mfma_f32_16x16x32_f16 v[38:41], v[138:141], v[170:173], v[38:41]
	v_mfma_f32_16x16x32_f16 v[38:41], v[142:145], v[174:177], v[38:41]
	v_mfma_f32_16x16x32_f16 v[26:29], v[134:137], v[174:177], v[26:29]
	v_mfma_f32_16x16x32_f16 v[26:29], v[130:133], v[170:173], v[26:29]
	v_mfma_f32_16x16x32_f16 v[10:13], v[130:133], v[162:165], v[10:13]
	v_mfma_f32_16x16x32_f16 v[10:13], v[134:137], v[166:169], v[10:13]
	v_mfma_f32_16x16x32_f16 v[22:25], v[142:145], v[166:169], v[22:25]
	v_mfma_f32_16x16x32_f16 v[22:25], v[138:141], v[162:165], v[22:25]
	s_barrier
	s_setprio 0
	s_add_i32 s64, s64, 2
	s_add_u32 s53, s53, 0x100
	s_addc_u32 s61, s61, 0
	s_cmp_gt_u32 s64, 13
	s_cbranch_scc1 .LBB0_241
.LBB0_231:
	ds_read_b128 v[146:149], v236
	ds_read_b128 v[150:153], v236 offset:1024
	ds_read_b128 v[154:157], v236 offset:2048
	ds_read_b128 v[158:161], v236 offset:3072
	ds_read_b128 v[130:133], v237
	ds_read_b128 v[134:137], v237 offset:1024
	ds_read_b128 v[138:141], v237 offset:2048
	ds_read_b128 v[142:145], v237 offset:3072
	s_mov_b64 s[6:7], s[8:9]
	s_add_u32 s8, s6, 0x100
	s_addc_u32 s9, s7, 0
	s_cmp_eq_u32 s64, 12
	s_cselect_b64 s[62:63], -1, 0
	s_and_b64 s[24:25], s[62:63], exec
	s_cselect_b32 s27, s11, s9
	s_cselect_b32 s26, s35, s8
	s_cselect_b32 s25, s1, s61
	s_cselect_b32 s24, s46, s53
	ds_read_b128 v[162:165], v238
	ds_read_b128 v[166:169], v238 offset:1024
	ds_read_b128 v[170:173], v238 offset:2048
	ds_read_b128 v[174:177], v238 offset:3072
	ds_read_b128 v[178:181], v238 offset:4096
	ds_read_b128 v[182:185], v238 offset:5120
	ds_read_b128 v[186:189], v238 offset:6144
	ds_read_b128 v[190:193], v238 offset:7168
	s_add_u32 s6, s6, 0x40080
	s_addc_u32 s7, s7, 0
	s_add_u32 m0, s28, 0xc000
	s_nop 0
	global_load_lds_dwordx4 v232, s[6:7]
	s_nop 0
	s_add_u32 m0, s28, 0xe000
	s_nop 0
	global_load_lds_dwordx4 v234, s[6:7]
	s_waitcnt vmcnt(8)
	s_waitcnt lgkmcnt(0)
	s_barrier
	v_mfma_f32_16x16x32_f16 v[118:121], v[146:149], v[162:165], v[118:121]
	s_setprio 1
	v_mfma_f32_16x16x32_f16 v[118:121], v[150:153], v[166:169], v[118:121]
	v_mfma_f32_16x16x32_f16 v[114:117], v[158:161], v[166:169], v[114:117]
	v_mfma_f32_16x16x32_f16 v[114:117], v[154:157], v[162:165], v[114:117]
	v_mfma_f32_16x16x32_f16 v[98:101], v[154:157], v[170:173], v[98:101]
	v_mfma_f32_16x16x32_f16 v[98:101], v[158:161], v[174:177], v[98:101]
	v_mfma_f32_16x16x32_f16 v[102:105], v[150:153], v[174:177], v[102:105]
	v_mfma_f32_16x16x32_f16 v[102:105], v[146:149], v[170:173], v[102:105]
	v_mfma_f32_16x16x32_f16 v[86:89], v[146:149], v[178:181], v[86:89]
	v_mfma_f32_16x16x32_f16 v[86:89], v[150:153], v[182:185], v[86:89]
	v_mfma_f32_16x16x32_f16 v[78:81], v[158:161], v[182:185], v[78:81]
	v_mfma_f32_16x16x32_f16 v[78:81], v[154:157], v[178:181], v[78:81]
	v_mfma_f32_16x16x32_f16 v[50:53], v[154:157], v[186:189], v[50:53]
	v_mfma_f32_16x16x32_f16 v[50:53], v[158:161], v[190:193], v[50:53]
	v_mfma_f32_16x16x32_f16 v[58:61], v[150:153], v[190:193], v[58:61]
	v_mfma_f32_16x16x32_f16 v[58:61], v[146:149], v[186:189], v[58:61]
	v_mfma_f32_16x16x32_f16 v[126:129], v[130:133], v[162:165], v[126:129]
	v_mfma_f32_16x16x32_f16 v[126:129], v[134:137], v[166:169], v[126:129]
	v_mfma_f32_16x16x32_f16 v[122:125], v[142:145], v[166:169], v[122:125]
	v_mfma_f32_16x16x32_f16 v[122:125], v[138:141], v[162:165], v[122:125]
	v_mfma_f32_16x16x32_f16 v[106:109], v[138:141], v[170:173], v[106:109]
	v_mfma_f32_16x16x32_f16 v[106:109], v[142:145], v[174:177], v[106:109]
	v_mfma_f32_16x16x32_f16 v[110:113], v[134:137], v[174:177], v[110:113]
	v_mfma_f32_16x16x32_f16 v[110:113], v[130:133], v[170:173], v[110:113]
	v_mfma_f32_16x16x32_f16 v[94:97], v[130:133], v[178:181], v[94:97]
	v_mfma_f32_16x16x32_f16 v[94:97], v[134:137], v[182:185], v[94:97]
	v_mfma_f32_16x16x32_f16 v[90:93], v[142:145], v[182:185], v[90:93]
	v_mfma_f32_16x16x32_f16 v[90:93], v[138:141], v[178:181], v[90:93]
	v_mfma_f32_16x16x32_f16 v[66:69], v[138:141], v[186:189], v[66:69]
	v_mfma_f32_16x16x32_f16 v[66:69], v[142:145], v[190:193], v[66:69]
	v_mfma_f32_16x16x32_f16 v[74:77], v[134:137], v[190:193], v[74:77]
	v_mfma_f32_16x16x32_f16 v[74:77], v[130:133], v[186:189], v[74:77]
	s_barrier
	s_setprio 0
	ds_read_b128 v[186:189], v238 offset:16384
	ds_read_b128 v[190:193], v238 offset:17408
	ds_read_b128 v[178:181], v238 offset:18432
	ds_read_b128 v[182:185], v238 offset:19456
	ds_read_b128 v[170:173], v238 offset:20480
	ds_read_b128 v[174:177], v238 offset:21504
	ds_read_b128 v[162:165], v238 offset:22528
	ds_read_b128 v[166:169], v238 offset:23552
	s_and_b64 s[6:7], s[4:5], s[62:63]
	s_mov_b64 s[62:63], -1
	s_and_b64 vcc, exec, s[6:7]
	s_cbranch_vccnz .LBB0_233
	s_add_u32 m0, s28, 0x10000
	s_nop 0
	global_load_lds_dwordx4 v233, s[24:25]
	s_nop 0
	s_add_u32 m0, s28, 0x12000
	s_nop 0
	global_load_lds_dwordx4 v235, s[24:25]
	s_add_u32 s62, s24, 0x40000
	s_addc_u32 s63, s25, 0
	s_add_u32 m0, s28, 0x14000
	s_nop 0
	global_load_lds_dwordx4 v233, s[62:63]
	s_nop 0
	s_add_u32 m0, s28, 0x16000
	s_nop 0
	global_load_lds_dwordx4 v235, s[62:63]
	s_mov_b64 s[62:63], 0
	s_add_u32 m0, s28, 0
	s_nop 0
	global_load_lds_dwordx4 v232, s[26:27]
	s_nop 0
	s_add_u32 m0, s28, 0x2000
	s_nop 0
	global_load_lds_dwordx4 v234, s[26:27]
	s_waitcnt vmcnt(8)

; #define PG8_STAGE(bufoff, gbase, voff) do { if constexpr (ABL & 1) break; glds16s<(bufoff)>((voff)[0], (const void*)(gbase), ldsbw); glds16s<(bufoff) + 8192>((voff)[1], (const void*)(gbase), ldsbw); } while (0)
; #define PG8_LDA(dst, b, h) do { if constexpr (ABL & 4) break; _Pragma("unroll") for (int m = 0; m < 4; ++m) _Pragma("unroll") for (int k = 0; k < 2; ++k) dst[m][k] = *(const LAS f16x8*)(lds + PG8_SA(b, h) + aoff + m * 2048 + k * 1024); } while (0)
; #define PG8_LDB(dst, b, h) do { if constexpr (ABL & 4) break; _Pragma("unroll") for (int n = 0; n < 2; ++n) _Pragma("unroll") for (int k = 0; k < 2; ++k) dst[n][k] = *(const LAS f16x8*)(lds + PG8_SB(b, h) + boff + n * 2048 + k * 1024); } while (0)
; #define PG8_MMA(ai, bj, At, Bt) do { if constexpr (ABL & 2) break; __builtin_amdgcn_s_setprio(1); _Pragma("unroll") for (int m = 0; m < 4; ++m) _Pragma("unroll") for (int n = 0; n < 2; ++n) _Pragma("unroll") for (int k = 0; k < 2; ++k) \
;         acc[ai][bj][m][n] = __builtin_amdgcn_mfma_f32_16x16x32_f16(Bt[n][k], At[m][k], acc[ai][bj][m][n], 0, 0, 0); __builtin_amdgcn_s_setprio(0); } while (0)
; #define PG8_MMAF(ai, bj, At, Bt) do { if (t == 0) PG8_MMA0(ai, bj, At, Bt); else PG8_MMA(ai, bj, At, Bt); } while (0)
; #define PG8_WAIT_V(n) asm volatile("s_waitcnt vmcnt(" #n ")" ::: "memory")
; #define PG8_WAIT_L(n) asm volatile("s_waitcnt lgkmcnt(" #n ")" ::: "memory")
; #define PG8_BAR __builtin_amdgcn_s_barrier()
; #define PG8_SCHED __builtin_amdgcn_sched_barrier(0)
;     ...
;             if (!fin) PG8_WAIT_V(8); else PG8_WAIT_V(2); PG8_WAIT_L(0); PG8_BAR; PG8_MMAF(1, 0, At, B0); PG8_MMAF(1, 1, At, B1); PG8_BAR; PG8_SCHED;
;             PG8_LDB(B0, 1, 0); PG8_LDB(B1, 1, 1); PG8_SCHED; PG8_LDA(At, 1, 0); if (!fin) PG8_STAGE(PG8_SA(0, 1), a2 + hstep, voffA);
;             if (!fin) PG8_WAIT_V(8); else PG8_WAIT_V(0); PG8_WAIT_L(0); PG8_BAR; PG8_MMA(0, 0, At, B0); PG8_MMA(0, 1, At, B1); PG8_BAR; PG8_SCHED;
.LBB0_235:
	s_waitcnt lgkmcnt(0)
	s_xor_b64 s[62:63], s[6:7], -1
	s_barrier
	v_mfma_f32_16x16x32_f16 v[54:57], v[146:149], v[186:189], v[54:57]
	s_setprio 1
	v_mfma_f32_16x16x32_f16 v[54:57], v[150:153], v[190:193], v[54:57]
	v_mfma_f32_16x16x32_f16 v[46:49], v[158:161], v[190:193], v[46:49]
	v_mfma_f32_16x16x32_f16 v[46:49], v[154:157], v[186:189], v[46:49]
	v_mfma_f32_16x16x32_f16 v[30:33], v[154:157], v[178:181], v[30:33]
	v_mfma_f32_16x16x32_f16 v[30:33], v[158:161], v[182:185], v[30:33]
	v_mfma_f32_16x16x32_f16 v[34:37], v[150:153], v[182:185], v[34:37]
	v_mfma_f32_16x16x32_f16 v[34:37], v[146:149], v[178:181], v[34:37]
	v_mfma_f32_16x16x32_f16 v[18:21], v[146:149], v[170:173], v[18:21]
	v_mfma_f32_16x16x32_f16 v[18:21], v[150:153], v[174:177], v[18:21]
	v_mfma_f32_16x16x32_f16 v[14:17], v[158:161], v[174:177], v[14:17]
	v_mfma_f32_16x16x32_f16 v[14:17], v[154:157], v[170:173], v[14:17]
	v_mfma_f32_16x16x32_f16 v[2:5], v[154:157], v[162:165], v[2:5]
	v_mfma_f32_16x16x32_f16 v[2:5], v[158:161], v[166:169], v[2:5]
	v_mfma_f32_16x16x32_f16 v[6:9], v[150:153], v[166:169], v[6:9]
	v_mfma_f32_16x16x32_f16 v[6:9], v[146:149], v[162:165], v[6:9]
	v_mfma_f32_16x16x32_f16 v[82:85], v[130:133], v[186:189], v[82:85]
	v_mfma_f32_16x16x32_f16 v[82:85], v[134:137], v[190:193], v[82:85]
	v_mfma_f32_16x16x32_f16 v[70:73], v[142:145], v[190:193], v[70:73]
	v_mfma_f32_16x16x32_f16 v[70:73], v[138:141], v[186:189], v[70:73]
	v_mfma_f32_16x16x32_f16 v[42:45], v[138:141], v[178:181], v[42:45]
	v_mfma_f32_16x16x32_f16 v[42:45], v[142:145], v[182:185], v[42:45]
	v_mfma_f32_16x16x32_f16 v[62:65], v[134:137], v[182:185], v[62:65]
	v_mfma_f32_16x16x32_f16 v[62:65], v[130:133], v[178:181], v[62:65]
	v_mfma_f32_16x16x32_f16 v[38:41], v[130:133], v[170:173], v[38:41]
	v_mfma_f32_16x16x32_f16 v[38:41], v[134:137], v[174:177], v[38:41]
	v_mfma_f32_16x16x32_f16 v[26:29], v[142:145], v[174:177], v[26:29]
	v_mfma_f32_16x16x32_f16 v[26:29], v[138:141], v[170:173], v[26:29]
	v_mfma_f32_16x16x32_f16 v[10:13], v[138:141], v[162:165], v[10:13]
	v_mfma_f32_16x16x32_f16 v[10:13], v[142:145], v[166:169], v[10:13]
	v_mfma_f32_16x16x32_f16 v[22:25], v[134:137], v[166:169], v[22:25]
	v_mfma_f32_16x16x32_f16 v[22:25], v[130:133], v[162:165], v[22:25]
	s_barrier
	s_setprio 0
	ds_read_b128 v[154:157], v239
	ds_read_b128 v[158:161], v239 offset:1024
	ds_read_b128 v[146:149], v239 offset:2048
	ds_read_b128 v[150:153], v239 offset:3072
	ds_read_b128 v[138:141], v240
	ds_read_b128 v[142:145], v240 offset:1024
	ds_read_b128 v[130:133], v240 offset:2048
	ds_read_b128 v[134:137], v240 offset:3072
	ds_read_b128 v[186:189], v238 offset:32768
	ds_read_b128 v[190:193], v238 offset:33792
	ds_read_b128 v[178:181], v238 offset:34816
	ds_read_b128 v[182:185], v238 offset:35840
	ds_read_b128 v[170:173], v238 offset:36864
	ds_read_b128 v[174:177], v238 offset:37888
	ds_read_b128 v[162:165], v238 offset:38912
	ds_read_b128 v[166:169], v238 offset:39936
	v_cndmask_b32_e64 v198, 0, 1, s[62:63]
	v_cmp_ne_u32_e64 s[6:7], 1, v198
	s_andn2_b64 vcc, exec, s[62:63]
	s_mov_b64 s[62:63], -1
	s_cbranch_vccnz .LBB0_237
	s_add_u32 s62, s26, 0x40000
	s_addc_u32 s63, s27, 0
	s_add_u32 m0, s28, 0x4000
	s_nop 0
	global_load_lds_dwordx4 v232, s[62:63]
	s_nop 0
	s_add_u32 m0, s28, 0x6000
	s_nop 0
	global_load_lds_dwordx4 v234, s[62:63]
	s_waitcnt vmcnt(8)
	s_mov_b64 s[62:63], 0

; #define PG8_STAGE(bufoff, gbase, voff) do { if constexpr (ABL & 1) break; glds16s<(bufoff)>((voff)[0], (const void*)(gbase), ldsbw); glds16s<(bufoff) + 8192>((voff)[1], (const void*)(gbase), ldsbw); } while (0)
; #define PG8_LDA(dst, b, h) do { if constexpr (ABL & 4) break; _Pragma("unroll") for (int m = 0; m < 4; ++m) _Pragma("unroll") for (int k = 0; k < 2; ++k) dst[m][k] = *(const LAS f16x8*)(lds + PG8_SA(b, h) + aoff + m * 2048 + k * 1024); } while (0)
; #define PG8_MMA(ai, bj, At, Bt) do { if constexpr (ABL & 2) break; __builtin_amdgcn_s_setprio(1); _Pragma("unroll") for (int m = 0; m < 4; ++m) _Pragma("unroll") for (int n = 0; n < 2; ++n) _Pragma("unroll") for (int k = 0; k < 2; ++k) \
;         acc[ai][bj][m][n] = __builtin_amdgcn_mfma_f32_16x16x32_f16(Bt[n][k], At[m][k], acc[ai][bj][m][n], 0, 0, 0); __builtin_amdgcn_s_setprio(0); } while (0)
; #define PG8_WAIT_V(n) asm volatile("s_waitcnt vmcnt(" #n ")" ::: "memory")
; #define PG8_WAIT_L(n) asm volatile("s_waitcnt lgkmcnt(" #n ")" ::: "memory")
; #define PG8_BAR __builtin_amdgcn_s_barrier()
; #define PG8_SCHED __builtin_amdgcn_sched_barrier(0)
;     ...
;             if (!fin) PG8_WAIT_V(8); else PG8_WAIT_V(0); PG8_WAIT_L(0); PG8_BAR; PG8_MMA(0, 0, At, B0); PG8_MMA(0, 1, At, B1); PG8_BAR; PG8_SCHED;
;             PG8_LDA(At, 1, 1); if (!fin) { PG8_STAGE(PG8_SB(1, 0), b3, voffB); PG8_STAGE(PG8_SB(1, 1), b3 + hstep, voffB); PG8_STAGE(PG8_SA(1, 0), a3, voffA); }
;             if (!fin) PG8_WAIT_V(8); PG8_WAIT_L(0); PG8_BAR; PG8_MMA(1, 0, At, B0); PG8_MMA(1, 1, At, B1); PG8_BAR; PG8_SCHED;
.LBB0_239:
	s_waitcnt lgkmcnt(0)
	s_barrier
	v_mfma_f32_16x16x32_f16 v[118:121], v[154:157], v[186:189], v[118:121]
	s_setprio 1
	v_mfma_f32_16x16x32_f16 v[118:121], v[158:161], v[190:193], v[118:121]
	v_mfma_f32_16x16x32_f16 v[114:117], v[150:153], v[190:193], v[114:117]
	v_mfma_f32_16x16x32_f16 v[114:117], v[146:149], v[186:189], v[114:117]
	v_mfma_f32_16x16x32_f16 v[98:101], v[146:149], v[178:181], v[98:101]
	v_mfma_f32_16x16x32_f16 v[98:101], v[150:153], v[182:185], v[98:101]
	v_mfma_f32_16x16x32_f16 v[102:105], v[158:161], v[182:185], v[102:105]
	v_mfma_f32_16x16x32_f16 v[102:105], v[154:157], v[178:181], v[102:105]
	v_mfma_f32_16x16x32_f16 v[86:89], v[154:157], v[170:173], v[86:89]
	v_mfma_f32_16x16x32_f16 v[86:89], v[158:161], v[174:177], v[86:89]
	v_mfma_f32_16x16x32_f16 v[78:81], v[150:153], v[174:177], v[78:81]
	v_mfma_f32_16x16x32_f16 v[78:81], v[146:149], v[170:173], v[78:81]
	v_mfma_f32_16x16x32_f16 v[50:53], v[146:149], v[162:165], v[50:53]
	v_mfma_f32_16x16x32_f16 v[50:53], v[150:153], v[166:169], v[50:53]
	v_mfma_f32_16x16x32_f16 v[58:61], v[158:161], v[166:169], v[58:61]
	v_mfma_f32_16x16x32_f16 v[58:61], v[154:157], v[162:165], v[58:61]
	v_mfma_f32_16x16x32_f16 v[126:129], v[138:141], v[186:189], v[126:129]
	v_mfma_f32_16x16x32_f16 v[126:129], v[142:145], v[190:193], v[126:129]
	v_mfma_f32_16x16x32_f16 v[122:125], v[134:137], v[190:193], v[122:125]
	v_mfma_f32_16x16x32_f16 v[122:125], v[130:133], v[186:189], v[122:125]
	v_mfma_f32_16x16x32_f16 v[106:109], v[130:133], v[178:181], v[106:109]
	v_mfma_f32_16x16x32_f16 v[106:109], v[134:137], v[182:185], v[106:109]
	v_mfma_f32_16x16x32_f16 v[110:113], v[142:145], v[182:185], v[110:113]
	v_mfma_f32_16x16x32_f16 v[110:113], v[138:141], v[178:181], v[110:113]
	v_mfma_f32_16x16x32_f16 v[94:97], v[138:141], v[170:173], v[94:97]
	v_mfma_f32_16x16x32_f16 v[94:97], v[142:145], v[174:177], v[94:97]
	v_mfma_f32_16x16x32_f16 v[90:93], v[134:137], v[174:177], v[90:93]
	v_mfma_f32_16x16x32_f16 v[90:93], v[130:133], v[170:173], v[90:93]
	v_mfma_f32_16x16x32_f16 v[66:69], v[130:133], v[162:165], v[66:69]
	v_mfma_f32_16x16x32_f16 v[66:69], v[134:137], v[166:169], v[66:69]
	v_mfma_f32_16x16x32_f16 v[74:77], v[142:145], v[166:169], v[74:77]
	v_mfma_f32_16x16x32_f16 v[74:77], v[138:141], v[162:165], v[74:77]
	s_barrier
	s_setprio 0
	ds_read_b128 v[186:189], v238 offset:49152
	ds_read_b128 v[190:193], v238 offset:50176
	ds_read_b128 v[178:181], v238 offset:51200
	ds_read_b128 v[182:185], v238 offset:52224
	ds_read_b128 v[170:173], v238 offset:53248
	ds_read_b128 v[174:177], v238 offset:54272
	ds_read_b128 v[162:165], v238 offset:55296
	ds_read_b128 v[166:169], v238 offset:56320
	s_and_b64 vcc, exec, s[6:7]
	s_cbranch_vccnz .LBB0_230
	s_add_u32 s6, s26, 0x80
	s_addc_u32 s7, s27, 0
	s_add_u32 s26, s24, 0x80
	s_addc_u32 s27, s25, 0
	s_add_u32 m0, s28, 0x18000
	s_nop 0
	global_load_lds_dwordx4 v233, s[26:27]
	s_nop 0
	s_add_u32 m0, s28, 0x1a000
	s_nop 0
	global_load_lds_dwordx4 v235, s[26:27]
	s_add_u32 s24, s24, 0x40080
	s_addc_u32 s25, s25, 0
	s_add_u32 m0, s28, 0x1c000
	s_nop 0
	global_load_lds_dwordx4 v233, s[24:25]
	s_nop 0
	s_add_u32 m0, s28, 0x1e000
	s_nop 0
	global_load_lds_dwordx4 v235, s[24:25]
	s_nop 0
	s_add_u32 m0, s28, 0x8000
	s_nop 0
	global_load_lds_dwordx4 v232, s[6:7]
	s_nop 0
	s_add_u32 m0, s28, 0xa000
	s_nop 0
	global_load_lds_dwordx4 v234, s[6:7]
	s_waitcnt vmcnt(8)
	s_branch .LBB0_230

; #define PG8_STAGE(bufoff, gbase, voff) do { if constexpr (ABL & 1) break; glds16s<(bufoff)>((voff)[0], (const void*)(gbase), ldsbw); glds16s<(bufoff) + 8192>((voff)[1], (const void*)(gbase), ldsbw); } while (0)
; #define PG8_LDA(dst, b, h) do { if constexpr (ABL & 4) break; _Pragma("unroll") for (int m = 0; m < 4; ++m) _Pragma("unroll") for (int k = 0; k < 2; ++k) dst[m][k] = *(const LAS f16x8*)(lds + PG8_SA(b, h) + aoff + m * 2048 + k * 1024); } while (0)
; #define PG8_LDB(dst, b, h) do { if constexpr (ABL & 4) break; _Pragma("unroll") for (int n = 0; n < 2; ++n) _Pragma("unroll") for (int k = 0; k < 2; ++k) dst[n][k] = *(const LAS f16x8*)(lds + PG8_SB(b, h) + boff + n * 2048 + k * 1024); } while (0)
; #define PG8_BAR __builtin_amdgcn_s_barrier()
;     ...
;         for (int t = 0; t < nt; t += 2) {
;             const bool last = (t == nt - 2);
;             const char* a1 = cA + (size_t)(t + 1) * kstep;
;             const char* a2 = last ? nA : cA + (size_t)(t + 2) * kstep; const char* b2 = last ? nB : cB + (size_t)(t + 2) * kstep;
;             const char* a3 = a2 + kstep; const char* b3 = b2 + kstep;
;             if (last && has_next) S.a_ready(nxt);
;             if constexpr (SP2) {
;             PG8_LDB(B0, 0, 0); PG8_LDB(B1, 0, 1); PG8_SCHED; PG8_LDA(At, 0, 0); PG8_STAGE(PG8_SA(1, 1), a1 + hstep, voffA);
;             PG8_WAIT_V(8); PG8_WAIT_L(0); PG8_BAR; PG8_MMAF(0, 0, At, B0); PG8_MMAF(0, 1, At, B1); PG8_BAR; PG8_SCHED;
;             const bool fin = last && !has_next;
;             PG8_LDA(At, 0, 1); if (!fin) { PG8_STAGE(PG8_SB(0, 0), b2, voffB); PG8_STAGE(PG8_SB(0, 1), b2 + hstep, voffB); PG8_STAGE(PG8_SA(0, 0), a2, voffA); }
;             if (!fin) PG8_WAIT_V(8); else PG8_WAIT_V(2); PG8_WAIT_L(0); PG8_BAR; PG8_MMAF(1, 0, At, B0); PG8_MMAF(1, 1, At, B1); PG8_BAR; PG8_SCHED;
;             PG8_LDB(B0, 1, 0); PG8_LDB(B1, 1, 1); PG8_SCHED; PG8_LDA(At, 1, 0); if (!fin) PG8_STAGE(PG8_SA(0, 1), a2 + hstep, voffA);
;             if (!fin) PG8_WAIT_V(8); else PG8_WAIT_V(0); PG8_WAIT_L(0); PG8_BAR; PG8_MMA(0, 0, At, B0); PG8_MMA(0, 1, At, B1); PG8_BAR; PG8_SCHED;
;             PG8_LDA(At, 1, 1); if (!fin) { PG8_STAGE(PG8_SB(1, 0), b3, voffB); PG8_STAGE(PG8_SB(1, 1), b3 + hstep, voffB); PG8_STAGE(PG8_SA(1, 0), a3, voffA); }
;             if (!fin) PG8_WAIT_V(8); PG8_WAIT_L(0); PG8_BAR; PG8_MMA(1, 0, At, B0); PG8_MMA(1, 1, At, B1); PG8_BAR; PG8_SCHED;
.LBB0_749:
	s_waitcnt lgkmcnt(0)
	s_barrier
	v_mfma_f32_16x16x32_f16 v[62:65], v[162:165], v[186:189], v[62:65]
	s_setprio 1
	v_mfma_f32_16x16x32_f16 v[62:65], v[166:169], v[190:193], v[62:65]
	v_mfma_f32_16x16x32_f16 v[58:61], v[158:161], v[190:193], v[58:61]
	v_mfma_f32_16x16x32_f16 v[58:61], v[146:149], v[186:189], v[58:61]
	v_mfma_f32_16x16x32_f16 v[42:45], v[146:149], v[178:181], v[42:45]
	v_mfma_f32_16x16x32_f16 v[42:45], v[158:161], v[182:185], v[42:45]
	v_mfma_f32_16x16x32_f16 v[46:49], v[166:169], v[182:185], v[46:49]
	v_mfma_f32_16x16x32_f16 v[46:49], v[162:165], v[178:181], v[46:49]
	v_mfma_f32_16x16x32_f16 v[30:33], v[162:165], v[170:173], v[30:33]
	v_mfma_f32_16x16x32_f16 v[30:33], v[166:169], v[174:177], v[30:33]
	v_mfma_f32_16x16x32_f16 v[26:29], v[158:161], v[174:177], v[26:29]
	v_mfma_f32_16x16x32_f16 v[26:29], v[146:149], v[170:173], v[26:29]
	v_mfma_f32_16x16x32_f16 v[10:13], v[146:149], v[122:125], v[10:13]
	v_mfma_f32_16x16x32_f16 v[10:13], v[158:161], v[134:137], v[10:13]
	v_mfma_f32_16x16x32_f16 v[14:17], v[166:169], v[134:137], v[14:17]
	v_mfma_f32_16x16x32_f16 v[14:17], v[162:165], v[122:125], v[14:17]
	v_mfma_f32_16x16x32_f16 v[54:57], v[98:101], v[186:189], v[54:57]
	v_mfma_f32_16x16x32_f16 v[54:57], v[110:113], v[190:193], v[54:57]
	v_mfma_f32_16x16x32_f16 v[50:53], v[86:89], v[190:193], v[50:53]
	v_mfma_f32_16x16x32_f16 v[50:53], v[74:77], v[186:189], v[50:53]
	v_mfma_f32_16x16x32_f16 v[34:37], v[74:77], v[178:181], v[34:37]
	v_mfma_f32_16x16x32_f16 v[34:37], v[86:89], v[182:185], v[34:37]
	v_mfma_f32_16x16x32_f16 v[38:41], v[110:113], v[182:185], v[38:41]
	v_mfma_f32_16x16x32_f16 v[38:41], v[98:101], v[178:181], v[38:41]
	v_mfma_f32_16x16x32_f16 v[22:25], v[98:101], v[170:173], v[22:25]
	v_mfma_f32_16x16x32_f16 v[22:25], v[110:113], v[174:177], v[22:25]
	v_mfma_f32_16x16x32_f16 v[18:21], v[86:89], v[174:177], v[18:21]
	v_mfma_f32_16x16x32_f16 v[18:21], v[74:77], v[170:173], v[18:21]
	v_mfma_f32_16x16x32_f16 v[2:5], v[74:77], v[122:125], v[2:5]
	v_mfma_f32_16x16x32_f16 v[2:5], v[86:89], v[134:137], v[2:5]
	v_mfma_f32_16x16x32_f16 v[6:9], v[110:113], v[134:137], v[6:9]
	v_mfma_f32_16x16x32_f16 v[6:9], v[98:101], v[122:125], v[6:9]
	s_barrier
	s_setprio 0
	s_add_i32 s59, s59, 2
	s_add_u32 s30, s30, 0x100
	s_addc_u32 s31, s31, 0
	s_cmp_gt_u32 s59, 13
	s_cbranch_scc1 .LBB0_760
.LBB0_750:
	ds_read_b128 v[146:149], v222
	ds_read_b128 v[158:161], v222 offset:1024
	ds_read_b128 v[162:165], v222 offset:2048
	ds_read_b128 v[166:169], v222 offset:3072
	ds_read_b128 v[74:77], v223
	ds_read_b128 v[86:89], v223 offset:1024
	ds_read_b128 v[98:101], v223 offset:2048
	ds_read_b128 v[110:113], v223 offset:3072
	s_mov_b64 s[6:7], s[56:57]
	s_add_u32 s56, s6, 0x100
	s_addc_u32 s57, s7, 0
	s_cmp_eq_u32 s59, 12
	s_cselect_b64 s[26:27], -1, 0
	s_and_b64 s[8:9], s[26:27], exec
	s_cselect_b32 s25, s47, s57
	s_cselect_b32 s24, s55, s56
	s_cselect_b32 s9, s45, s31
	s_cselect_b32 s8, s58, s30
	ds_read_b128 v[170:173], v224
	ds_read_b128 v[174:177], v224 offset:1024
	ds_read_b128 v[178:181], v224 offset:2048
	ds_read_b128 v[182:185], v224 offset:3072
	ds_read_b128 v[186:189], v224 offset:4096
	ds_read_b128 v[190:193], v224 offset:5120
	ds_read_b128 v[194:197], v224 offset:6144
	ds_read_b128 v[198:201], v224 offset:7168
	s_add_u32 s6, s6, 0x40080
	s_addc_u32 s7, s7, 0
	s_add_u32 m0, s14, 0xc000
	s_nop 0
	global_load_lds_dwordx4 v1, s[6:7]
	s_nop 0
	s_add_u32 m0, s14, 0xe000
	s_nop 0
	global_load_lds_dwordx4 v213, s[6:7]
	s_waitcnt vmcnt(8)
	s_waitcnt lgkmcnt(0)
	s_barrier
	v_mfma_f32_16x16x32_f16 v[122:125], v[146:149], v[170:173], v[154:157]
	s_setprio 1
	v_mfma_f32_16x16x32_f16 v[122:125], v[158:161], v[174:177], v[122:125]
	v_mfma_f32_16x16x32_f16 v[134:137], v[162:165], v[170:173], v[150:153]
	v_mfma_f32_16x16x32_f16 v[134:137], v[166:169], v[174:177], v[134:137]
	v_mfma_f32_16x16x32_f16 v[130:133], v[146:149], v[178:181], v[130:133]
	v_mfma_f32_16x16x32_f16 v[130:133], v[158:161], v[182:185], v[130:133]
	v_mfma_f32_16x16x32_f16 v[126:129], v[162:165], v[178:181], v[126:129]
	v_mfma_f32_16x16x32_f16 v[126:129], v[166:169], v[182:185], v[126:129]
	v_mfma_f32_16x16x32_f16 v[106:109], v[146:149], v[186:189], v[106:109]
	v_mfma_f32_16x16x32_f16 v[106:109], v[158:161], v[190:193], v[106:109]
	v_mfma_f32_16x16x32_f16 v[102:105], v[162:165], v[186:189], v[102:105]
	v_mfma_f32_16x16x32_f16 v[102:105], v[166:169], v[190:193], v[102:105]
	v_mfma_f32_16x16x32_f16 v[82:85], v[146:149], v[194:197], v[82:85]
	v_mfma_f32_16x16x32_f16 v[82:85], v[158:161], v[198:201], v[82:85]
	v_mfma_f32_16x16x32_f16 v[78:81], v[162:165], v[194:197], v[78:81]
	v_mfma_f32_16x16x32_f16 v[78:81], v[166:169], v[198:201], v[78:81]
	v_mfma_f32_16x16x32_f16 v[142:145], v[74:77], v[170:173], v[142:145]
	v_mfma_f32_16x16x32_f16 v[142:145], v[86:89], v[174:177], v[142:145]
	v_mfma_f32_16x16x32_f16 v[138:141], v[110:113], v[174:177], v[138:141]
	v_mfma_f32_16x16x32_f16 v[138:141], v[98:101], v[170:173], v[138:141]
	v_mfma_f32_16x16x32_f16 v[114:117], v[98:101], v[178:181], v[114:117]
	v_mfma_f32_16x16x32_f16 v[114:117], v[110:113], v[182:185], v[114:117]
	v_mfma_f32_16x16x32_f16 v[118:121], v[86:89], v[182:185], v[118:121]
	v_mfma_f32_16x16x32_f16 v[118:121], v[74:77], v[178:181], v[118:121]
	v_mfma_f32_16x16x32_f16 v[94:97], v[74:77], v[186:189], v[94:97]
	v_mfma_f32_16x16x32_f16 v[94:97], v[86:89], v[190:193], v[94:97]
	v_mfma_f32_16x16x32_f16 v[90:93], v[110:113], v[190:193], v[90:93]
	v_mfma_f32_16x16x32_f16 v[90:93], v[98:101], v[186:189], v[90:93]
	v_mfma_f32_16x16x32_f16 v[66:69], v[98:101], v[194:197], v[66:69]
	v_mfma_f32_16x16x32_f16 v[66:69], v[110:113], v[198:201], v[66:69]
	v_mfma_f32_16x16x32_f16 v[70:73], v[86:89], v[198:201], v[70:73]
	v_mfma_f32_16x16x32_f16 v[70:73], v[74:77], v[194:197], v[70:73]
	s_barrier
	s_setprio 0
	ds_read_b128 v[186:189], v224 offset:16384
	ds_read_b128 v[190:193], v224 offset:17408
	ds_read_b128 v[178:181], v224 offset:18432
	ds_read_b128 v[182:185], v224 offset:19456
	ds_read_b128 v[170:173], v224 offset:20480
	ds_read_b128 v[174:177], v224 offset:21504
	ds_read_b128 v[150:153], v224 offset:22528
	ds_read_b128 v[154:157], v224 offset:23552
	s_and_b64 s[6:7], s[4:5], s[26:27]
	s_mov_b64 s[26:27], -1
	s_and_b64 vcc, exec, s[6:7]
	s_cbranch_vccnz .LBB0_752
	s_add_u32 m0, s14, 0x10000
	s_nop 0
	global_load_lds_dwordx4 v209, s[8:9]
	s_nop 0
	s_add_u32 m0, s14, 0x12000
	s_nop 0
	global_load_lds_dwordx4 v219, s[8:9]
	s_add_u32 s26, s8, 0x40000
	s_addc_u32 s27, s9, 0
	s_add_u32 m0, s14, 0x14000
	s_nop 0
	global_load_lds_dwordx4 v209, s[26:27]
	s_nop 0
	s_add_u32 m0, s14, 0x16000
	s_nop 0
	global_load_lds_dwordx4 v219, s[26:27]
	s_mov_b64 s[26:27], 0
	s_add_u32 m0, s14, 0
	s_nop 0
	global_load_lds_dwordx4 v1, s[24:25]
	s_nop 0
	s_add_u32 m0, s14, 0x2000
	s_nop 0
	global_load_lds_dwordx4 v213, s[24:25]
	s_waitcnt vmcnt(8)

; #define PG8_STAGE(bufoff, gbase, voff) do { if constexpr (ABL & 1) break; glds16s<(bufoff)>((voff)[0], (const void*)(gbase), ldsbw); glds16s<(bufoff) + 8192>((voff)[1], (const void*)(gbase), ldsbw); } while (0)
; #define PG8_LDA(dst, b, h) do { if constexpr (ABL & 4) break; _Pragma("unroll") for (int m = 0; m < 4; ++m) _Pragma("unroll") for (int k = 0; k < 2; ++k) dst[m][k] = *(const LAS f16x8*)(lds + PG8_SA(b, h) + aoff + m * 2048 + k * 1024); } while (0)
; #define PG8_LDB(dst, b, h) do { if constexpr (ABL & 4) break; _Pragma("unroll") for (int n = 0; n < 2; ++n) _Pragma("unroll") for (int k = 0; k < 2; ++k) dst[n][k] = *(const LAS f16x8*)(lds + PG8_SB(b, h) + boff + n * 2048 + k * 1024); } while (0)
; #define PG8_MMA(ai, bj, At, Bt) do { if constexpr (ABL & 2) break; __builtin_amdgcn_s_setprio(1); _Pragma("unroll") for (int m = 0; m < 4; ++m) _Pragma("unroll") for (int n = 0; n < 2; ++n) _Pragma("unroll") for (int k = 0; k < 2; ++k) \
;         acc[ai][bj][m][n] = __builtin_amdgcn_mfma_f32_16x16x32_f16(Bt[n][k], At[m][k], acc[ai][bj][m][n], 0, 0, 0); __builtin_amdgcn_s_setprio(0); } while (0)
; #define PG8_MMAF(ai, bj, At, Bt) do { if (t == 0) PG8_MMA0(ai, bj, At, Bt); else PG8_MMA(ai, bj, At, Bt); } while (0)
; #define PG8_WAIT_V(n) asm volatile("s_waitcnt vmcnt(" #n ")" ::: "memory")
; #define PG8_WAIT_L(n) asm volatile("s_waitcnt lgkmcnt(" #n ")" ::: "memory")
; #define PG8_BAR __builtin_amdgcn_s_barrier()
; #define PG8_SCHED __builtin_amdgcn_sched_barrier(0)
;     ...
;             if (!fin) PG8_WAIT_V(8); else PG8_WAIT_V(2); PG8_WAIT_L(0); PG8_BAR; PG8_MMAF(1, 0, At, B0); PG8_MMAF(1, 1, At, B1); PG8_BAR; PG8_SCHED;
;             PG8_LDB(B0, 1, 0); PG8_LDB(B1, 1, 1); PG8_SCHED; PG8_LDA(At, 1, 0); if (!fin) PG8_STAGE(PG8_SA(0, 1), a2 + hstep, voffA);
;             if (!fin) PG8_WAIT_V(8); else PG8_WAIT_V(0); PG8_WAIT_L(0); PG8_BAR; PG8_MMA(0, 0, At, B0); PG8_MMA(0, 1, At, B1); PG8_BAR; PG8_SCHED;
.LBB0_754:
	s_waitcnt lgkmcnt(0)
	s_xor_b64 s[26:27], s[6:7], -1
	s_barrier
	v_mfma_f32_16x16x32_f16 v[62:65], v[146:149], v[186:189], v[62:65]
	s_setprio 1
	v_mfma_f32_16x16x32_f16 v[62:65], v[158:161], v[190:193], v[62:65]
	v_mfma_f32_16x16x32_f16 v[58:61], v[166:169], v[190:193], v[58:61]
	v_mfma_f32_16x16x32_f16 v[58:61], v[162:165], v[186:189], v[58:61]
	v_mfma_f32_16x16x32_f16 v[42:45], v[162:165], v[178:181], v[42:45]
	v_mfma_f32_16x16x32_f16 v[42:45], v[166:169], v[182:185], v[42:45]
	v_mfma_f32_16x16x32_f16 v[46:49], v[158:161], v[182:185], v[46:49]
	v_mfma_f32_16x16x32_f16 v[46:49], v[146:149], v[178:181], v[46:49]
	v_mfma_f32_16x16x32_f16 v[30:33], v[146:149], v[170:173], v[30:33]
	v_mfma_f32_16x16x32_f16 v[30:33], v[158:161], v[174:177], v[30:33]
	v_mfma_f32_16x16x32_f16 v[26:29], v[166:169], v[174:177], v[26:29]
	v_mfma_f32_16x16x32_f16 v[26:29], v[162:165], v[170:173], v[26:29]
	v_mfma_f32_16x16x32_f16 v[10:13], v[162:165], v[150:153], v[10:13]
	v_mfma_f32_16x16x32_f16 v[10:13], v[166:169], v[154:157], v[10:13]
	v_mfma_f32_16x16x32_f16 v[14:17], v[158:161], v[154:157], v[14:17]
	v_mfma_f32_16x16x32_f16 v[14:17], v[146:149], v[150:153], v[14:17]
	v_mfma_f32_16x16x32_f16 v[54:57], v[74:77], v[186:189], v[54:57]
	v_mfma_f32_16x16x32_f16 v[54:57], v[86:89], v[190:193], v[54:57]
	v_mfma_f32_16x16x32_f16 v[50:53], v[110:113], v[190:193], v[50:53]
	v_mfma_f32_16x16x32_f16 v[50:53], v[98:101], v[186:189], v[50:53]
	v_mfma_f32_16x16x32_f16 v[34:37], v[98:101], v[178:181], v[34:37]
	v_mfma_f32_16x16x32_f16 v[34:37], v[110:113], v[182:185], v[34:37]
	v_mfma_f32_16x16x32_f16 v[38:41], v[86:89], v[182:185], v[38:41]
	v_mfma_f32_16x16x32_f16 v[38:41], v[74:77], v[178:181], v[38:41]
	v_mfma_f32_16x16x32_f16 v[22:25], v[74:77], v[170:173], v[22:25]
	v_mfma_f32_16x16x32_f16 v[22:25], v[86:89], v[174:177], v[22:25]
	v_mfma_f32_16x16x32_f16 v[18:21], v[110:113], v[174:177], v[18:21]
	v_mfma_f32_16x16x32_f16 v[18:21], v[98:101], v[170:173], v[18:21]
	v_mfma_f32_16x16x32_f16 v[2:5], v[98:101], v[150:153], v[2:5]
	v_mfma_f32_16x16x32_f16 v[2:5], v[110:113], v[154:157], v[2:5]
	v_mfma_f32_16x16x32_f16 v[6:9], v[86:89], v[154:157], v[6:9]
	v_mfma_f32_16x16x32_f16 v[6:9], v[74:77], v[150:153], v[6:9]
	s_barrier
	s_setprio 0
	ds_read_b128 v[162:165], v225
	ds_read_b128 v[166:169], v225 offset:1024
	ds_read_b128 v[146:149], v225 offset:2048
	ds_read_b128 v[158:161], v225 offset:3072
	ds_read_b128 v[98:101], v226
	ds_read_b128 v[110:113], v226 offset:1024
	ds_read_b128 v[74:77], v226 offset:2048
	ds_read_b128 v[86:89], v226 offset:3072
	ds_read_b128 v[194:197], v224 offset:32768
	ds_read_b128 v[198:201], v224 offset:33792
	ds_read_b128 v[186:189], v224 offset:34816
	ds_read_b128 v[190:193], v224 offset:35840
	ds_read_b128 v[178:181], v224 offset:36864
	ds_read_b128 v[182:185], v224 offset:37888
	ds_read_b128 v[170:173], v224 offset:38912
	ds_read_b128 v[174:177], v224 offset:39936
	v_cndmask_b32_e64 v150, 0, 1, s[26:27]
	v_cmp_ne_u32_e64 s[6:7], 1, v150
	s_andn2_b64 vcc, exec, s[26:27]
	s_mov_b64 s[26:27], -1
	s_cbranch_vccnz .LBB0_756
	s_add_u32 s26, s24, 0x40000
	s_addc_u32 s27, s25, 0
	s_add_u32 m0, s14, 0x4000
	s_nop 0
	global_load_lds_dwordx4 v1, s[26:27]
	s_nop 0
	s_add_u32 m0, s14, 0x6000
	s_nop 0
	global_load_lds_dwordx4 v213, s[26:27]
	s_waitcnt vmcnt(8)
	s_mov_b64 s[26:27], 0

; #define PG8_STAGE(bufoff, gbase, voff) do { if constexpr (ABL & 1) break; glds16s<(bufoff)>((voff)[0], (const void*)(gbase), ldsbw); glds16s<(bufoff) + 8192>((voff)[1], (const void*)(gbase), ldsbw); } while (0)
; #define PG8_LDA(dst, b, h) do { if constexpr (ABL & 4) break; _Pragma("unroll") for (int m = 0; m < 4; ++m) _Pragma("unroll") for (int k = 0; k < 2; ++k) dst[m][k] = *(const LAS f16x8*)(lds + PG8_SA(b, h) + aoff + m * 2048 + k * 1024); } while (0)
; #define PG8_LDB(dst, b, h) do { if constexpr (ABL & 4) break; _Pragma("unroll") for (int n = 0; n < 2; ++n) _Pragma("unroll") for (int k = 0; k < 2; ++k) dst[n][k] = *(const LAS f16x8*)(lds + PG8_SB(b, h) + boff + n * 2048 + k * 1024); } while (0)
; #define PG8_BAR __builtin_amdgcn_s_barrier()
;     ...
;         for (int t = 0; t < nt; t += 2) {
;             const bool last = (t == nt - 2);
;             const char* a1 = cA + (size_t)(t + 1) * kstep;
;             const char* a2 = last ? nA : cA + (size_t)(t + 2) * kstep; const char* b2 = last ? nB : cB + (size_t)(t + 2) * kstep;
;             const char* a3 = a2 + kstep; const char* b3 = b2 + kstep;
;             if (last && has_next) S.a_ready(nxt);
;             if constexpr (SP2) {
;             PG8_LDB(B0, 0, 0); PG8_LDB(B1, 0, 1); PG8_SCHED; PG8_LDA(At, 0, 0); PG8_STAGE(PG8_SA(1, 1), a1 + hstep, voffA);
;             PG8_WAIT_V(8); PG8_WAIT_L(0); PG8_BAR; PG8_MMAF(0, 0, At, B0); PG8_MMAF(0, 1, At, B1); PG8_BAR; PG8_SCHED;
;             const bool fin = last && !has_next;
;             PG8_LDA(At, 0, 1); if (!fin) { PG8_STAGE(PG8_SB(0, 0), b2, voffB); PG8_STAGE(PG8_SB(0, 1), b2 + hstep, voffB); PG8_STAGE(PG8_SA(0, 0), a2, voffA); }
;             if (!fin) PG8_WAIT_V(8); else PG8_WAIT_V(2); PG8_WAIT_L(0); PG8_BAR; PG8_MMAF(1, 0, At, B0); PG8_MMAF(1, 1, At, B1); PG8_BAR; PG8_SCHED;
;             PG8_LDB(B0, 1, 0); PG8_LDB(B1, 1, 1); PG8_SCHED; PG8_LDA(At, 1, 0); if (!fin) PG8_STAGE(PG8_SA(0, 1), a2 + hstep, voffA);
;             if (!fin) PG8_WAIT_V(8); else PG8_WAIT_V(0); PG8_WAIT_L(0); PG8_BAR; PG8_MMA(0, 0, At, B0); PG8_MMA(0, 1, At, B1); PG8_BAR; PG8_SCHED;
;             PG8_LDA(At, 1, 1); if (!fin) { PG8_STAGE(PG8_SB(1, 0), b3, voffB); PG8_STAGE(PG8_SB(1, 1), b3 + hstep, voffB); PG8_STAGE(PG8_SA(1, 0), a3, voffA); }
;             if (!fin) PG8_WAIT_V(8); PG8_WAIT_L(0); PG8_BAR; PG8_MMA(1, 0, At, B0); PG8_MMA(1, 1, At, B1); PG8_BAR; PG8_SCHED;
.LBB0_842:
	s_waitcnt lgkmcnt(0)
	s_barrier
	v_mfma_f32_16x16x32_f16 v[58:61], v[146:149], v[186:189], v[58:61]
	s_setprio 1
	v_mfma_f32_16x16x32_f16 v[58:61], v[150:153], v[190:193], v[58:61]
	v_mfma_f32_16x16x32_f16 v[50:53], v[158:161], v[190:193], v[50:53]
	v_mfma_f32_16x16x32_f16 v[50:53], v[154:157], v[186:189], v[50:53]
	v_mfma_f32_16x16x32_f16 v[34:37], v[154:157], v[178:181], v[34:37]
	v_mfma_f32_16x16x32_f16 v[34:37], v[158:161], v[182:185], v[34:37]
	v_mfma_f32_16x16x32_f16 v[42:45], v[150:153], v[182:185], v[42:45]
	v_mfma_f32_16x16x32_f16 v[42:45], v[146:149], v[178:181], v[42:45]
	v_mfma_f32_16x16x32_f16 v[26:29], v[146:149], v[170:173], v[26:29]
	v_mfma_f32_16x16x32_f16 v[26:29], v[150:153], v[174:177], v[26:29]
	v_mfma_f32_16x16x32_f16 v[18:21], v[158:161], v[174:177], v[18:21]
	v_mfma_f32_16x16x32_f16 v[18:21], v[154:157], v[170:173], v[18:21]
	v_mfma_f32_16x16x32_f16 v[2:5], v[154:157], v[162:165], v[2:5]
	v_mfma_f32_16x16x32_f16 v[2:5], v[158:161], v[166:169], v[2:5]
	v_mfma_f32_16x16x32_f16 v[10:13], v[150:153], v[166:169], v[10:13]
	v_mfma_f32_16x16x32_f16 v[10:13], v[146:149], v[162:165], v[10:13]
	v_mfma_f32_16x16x32_f16 v[66:69], v[130:133], v[186:189], v[66:69]
	v_mfma_f32_16x16x32_f16 v[66:69], v[134:137], v[190:193], v[66:69]
	v_mfma_f32_16x16x32_f16 v[54:57], v[142:145], v[190:193], v[54:57]
	v_mfma_f32_16x16x32_f16 v[54:57], v[138:141], v[186:189], v[54:57]
	v_mfma_f32_16x16x32_f16 v[38:41], v[138:141], v[178:181], v[38:41]
	v_mfma_f32_16x16x32_f16 v[38:41], v[142:145], v[182:185], v[38:41]
	v_mfma_f32_16x16x32_f16 v[46:49], v[134:137], v[182:185], v[46:49]
	v_mfma_f32_16x16x32_f16 v[46:49], v[130:133], v[178:181], v[46:49]
	v_mfma_f32_16x16x32_f16 v[30:33], v[130:133], v[170:173], v[30:33]
	v_mfma_f32_16x16x32_f16 v[30:33], v[134:137], v[174:177], v[30:33]
	v_mfma_f32_16x16x32_f16 v[22:25], v[142:145], v[174:177], v[22:25]
	v_mfma_f32_16x16x32_f16 v[22:25], v[138:141], v[170:173], v[22:25]
	v_mfma_f32_16x16x32_f16 v[6:9], v[138:141], v[162:165], v[6:9]
	v_mfma_f32_16x16x32_f16 v[6:9], v[142:145], v[166:169], v[6:9]
	v_mfma_f32_16x16x32_f16 v[14:17], v[134:137], v[166:169], v[14:17]
	v_mfma_f32_16x16x32_f16 v[14:17], v[130:133], v[162:165], v[14:17]
	s_barrier
	s_setprio 0
	s_add_i32 s55, s55, 2
	s_add_u32 s53, s53, 0x100
	s_addc_u32 s54, s54, 0
	s_cmp_gt_u32 s55, 13
	s_cbranch_scc1 .LBB0_853
.LBB0_843:
	ds_read_b128 v[146:149], v210
	ds_read_b128 v[150:153], v210 offset:1024
	ds_read_b128 v[154:157], v210 offset:2048
	ds_read_b128 v[158:161], v210 offset:3072
	ds_read_b128 v[130:133], v211
	ds_read_b128 v[134:137], v211 offset:1024
	ds_read_b128 v[138:141], v211 offset:2048
	ds_read_b128 v[142:145], v211 offset:3072
	s_mov_b64 s[6:7], s[48:49]
	s_add_u32 s48, s6, 0x100
	s_addc_u32 s49, s7, 0
	s_cmp_eq_u32 s55, 12
	s_cselect_b64 s[26:27], -1, 0
	s_and_b64 s[8:9], s[26:27], exec
	s_cselect_b32 s25, s41, s49
	s_cselect_b32 s24, s51, s48
	s_cselect_b32 s9, s39, s54
	s_cselect_b32 s8, s52, s53
	ds_read_b128 v[162:165], v212
	ds_read_b128 v[166:169], v212 offset:1024
	ds_read_b128 v[170:173], v212 offset:2048
	ds_read_b128 v[174:177], v212 offset:3072
	ds_read_b128 v[178:181], v212 offset:4096
	ds_read_b128 v[182:185], v212 offset:5120
	ds_read_b128 v[186:189], v212 offset:6144
	ds_read_b128 v[190:193], v212 offset:7168
	s_add_u32 s6, s6, 0x40080
	s_addc_u32 s7, s7, 0
	s_add_u32 m0, s14, 0xc000
	s_nop 0
	global_load_lds_dwordx4 v206, s[6:7]
	s_nop 0
	s_add_u32 m0, s14, 0xe000
	s_nop 0
	global_load_lds_dwordx4 v208, s[6:7]
	s_waitcnt vmcnt(8)
	s_waitcnt lgkmcnt(0)
	s_barrier
	v_mfma_f32_16x16x32_f16 v[114:117], v[146:149], v[162:165], v[114:117]
	s_setprio 1
	v_mfma_f32_16x16x32_f16 v[114:117], v[150:153], v[166:169], v[114:117]
	v_mfma_f32_16x16x32_f16 v[110:113], v[158:161], v[166:169], v[110:113]
	v_mfma_f32_16x16x32_f16 v[110:113], v[154:157], v[162:165], v[110:113]
	v_mfma_f32_16x16x32_f16 v[98:101], v[154:157], v[170:173], v[98:101]
	v_mfma_f32_16x16x32_f16 v[98:101], v[158:161], v[174:177], v[98:101]
	v_mfma_f32_16x16x32_f16 v[106:109], v[150:153], v[174:177], v[106:109]
	v_mfma_f32_16x16x32_f16 v[106:109], v[146:149], v[170:173], v[106:109]
	v_mfma_f32_16x16x32_f16 v[90:93], v[146:149], v[178:181], v[90:93]
	v_mfma_f32_16x16x32_f16 v[90:93], v[150:153], v[182:185], v[90:93]
	v_mfma_f32_16x16x32_f16 v[82:85], v[158:161], v[182:185], v[82:85]
	v_mfma_f32_16x16x32_f16 v[82:85], v[154:157], v[178:181], v[82:85]
	v_mfma_f32_16x16x32_f16 v[62:65], v[154:157], v[186:189], v[62:65]
	v_mfma_f32_16x16x32_f16 v[62:65], v[158:161], v[190:193], v[62:65]
	v_mfma_f32_16x16x32_f16 v[74:77], v[150:153], v[190:193], v[74:77]
	v_mfma_f32_16x16x32_f16 v[74:77], v[146:149], v[186:189], v[74:77]
	v_mfma_f32_16x16x32_f16 v[126:129], v[130:133], v[162:165], v[126:129]
	v_mfma_f32_16x16x32_f16 v[126:129], v[134:137], v[166:169], v[126:129]
	v_mfma_f32_16x16x32_f16 v[122:125], v[142:145], v[166:169], v[122:125]
	v_mfma_f32_16x16x32_f16 v[122:125], v[138:141], v[162:165], v[122:125]
	v_mfma_f32_16x16x32_f16 v[102:105], v[138:141], v[170:173], v[102:105]
	v_mfma_f32_16x16x32_f16 v[102:105], v[142:145], v[174:177], v[102:105]
	v_mfma_f32_16x16x32_f16 v[118:121], v[134:137], v[174:177], v[118:121]
	v_mfma_f32_16x16x32_f16 v[118:121], v[130:133], v[170:173], v[118:121]
	v_mfma_f32_16x16x32_f16 v[94:97], v[130:133], v[178:181], v[94:97]
	v_mfma_f32_16x16x32_f16 v[94:97], v[134:137], v[182:185], v[94:97]
	v_mfma_f32_16x16x32_f16 v[86:89], v[142:145], v[182:185], v[86:89]
	v_mfma_f32_16x16x32_f16 v[86:89], v[138:141], v[178:181], v[86:89]
	v_mfma_f32_16x16x32_f16 v[70:73], v[138:141], v[186:189], v[70:73]
	v_mfma_f32_16x16x32_f16 v[70:73], v[142:145], v[190:193], v[70:73]
	v_mfma_f32_16x16x32_f16 v[78:81], v[134:137], v[190:193], v[78:81]
	v_mfma_f32_16x16x32_f16 v[78:81], v[130:133], v[186:189], v[78:81]
	s_barrier
	s_setprio 0
	ds_read_b128 v[186:189], v212 offset:16384
	ds_read_b128 v[190:193], v212 offset:17408
	ds_read_b128 v[178:181], v212 offset:18432
	ds_read_b128 v[182:185], v212 offset:19456
	ds_read_b128 v[170:173], v212 offset:20480
	ds_read_b128 v[174:177], v212 offset:21504
	ds_read_b128 v[162:165], v212 offset:22528
	ds_read_b128 v[166:169], v212 offset:23552
	s_and_b64 s[6:7], s[4:5], s[26:27]
	s_mov_b64 s[26:27], -1
	s_and_b64 vcc, exec, s[6:7]
	s_cbranch_vccnz .LBB0_845
	s_add_u32 m0, s14, 0x10000
	s_nop 0
	global_load_lds_dwordx4 v207, s[8:9]
	s_nop 0
	s_add_u32 m0, s14, 0x12000
	s_nop 0
	global_load_lds_dwordx4 v209, s[8:9]
	s_add_u32 s26, s8, 0x40000
	s_addc_u32 s27, s9, 0
	s_add_u32 m0, s14, 0x14000
	s_nop 0
	global_load_lds_dwordx4 v207, s[26:27]
	s_nop 0
	s_add_u32 m0, s14, 0x16000
	s_nop 0
	global_load_lds_dwordx4 v209, s[26:27]
	s_mov_b64 s[26:27], 0
	s_add_u32 m0, s14, 0
	s_nop 0
	global_load_lds_dwordx4 v206, s[24:25]
	s_nop 0
	s_add_u32 m0, s14, 0x2000
	s_nop 0
	global_load_lds_dwordx4 v208, s[24:25]
	s_waitcnt vmcnt(8)

; #define PG8_STAGE(bufoff, gbase, voff) do { if constexpr (ABL & 1) break; glds16s<(bufoff)>((voff)[0], (const void*)(gbase), ldsbw); glds16s<(bufoff) + 8192>((voff)[1], (const void*)(gbase), ldsbw); } while (0)
; #define PG8_LDA(dst, b, h) do { if constexpr (ABL & 4) break; _Pragma("unroll") for (int m = 0; m < 4; ++m) _Pragma("unroll") for (int k = 0; k < 2; ++k) dst[m][k] = *(const LAS f16x8*)(lds + PG8_SA(b, h) + aoff + m * 2048 + k * 1024); } while (0)
; #define PG8_LDB(dst, b, h) do { if constexpr (ABL & 4) break; _Pragma("unroll") for (int n = 0; n < 2; ++n) _Pragma("unroll") for (int k = 0; k < 2; ++k) dst[n][k] = *(const LAS f16x8*)(lds + PG8_SB(b, h) + boff + n * 2048 + k * 1024); } while (0)
; #define PG8_MMA(ai, bj, At, Bt) do { if constexpr (ABL & 2) break; __builtin_amdgcn_s_setprio(1); _Pragma("unroll") for (int m = 0; m < 4; ++m) _Pragma("unroll") for (int n = 0; n < 2; ++n) _Pragma("unroll") for (int k = 0; k < 2; ++k) \
;         acc[ai][bj][m][n] = __builtin_amdgcn_mfma_f32_16x16x32_f16(Bt[n][k], At[m][k], acc[ai][bj][m][n], 0, 0, 0); __builtin_amdgcn_s_setprio(0); } while (0)
; #define PG8_MMAF(ai, bj, At, Bt) do { if (t == 0) PG8_MMA0(ai, bj, At, Bt); else PG8_MMA(ai, bj, At, Bt); } while (0)
; #define PG8_WAIT_V(n) asm volatile("s_waitcnt vmcnt(" #n ")" ::: "memory")
; #define PG8_WAIT_L(n) asm volatile("s_waitcnt lgkmcnt(" #n ")" ::: "memory")
; #define PG8_BAR __builtin_amdgcn_s_barrier()
; #define PG8_SCHED __builtin_amdgcn_sched_barrier(0)
;     ...
;             if (!fin) PG8_WAIT_V(8); else PG8_WAIT_V(2); PG8_WAIT_L(0); PG8_BAR; PG8_MMAF(1, 0, At, B0); PG8_MMAF(1, 1, At, B1); PG8_BAR; PG8_SCHED;
;             PG8_LDB(B0, 1, 0); PG8_LDB(B1, 1, 1); PG8_SCHED; PG8_LDA(At, 1, 0); if (!fin) PG8_STAGE(PG8_SA(0, 1), a2 + hstep, voffA);
;             if (!fin) PG8_WAIT_V(8); else PG8_WAIT_V(0); PG8_WAIT_L(0); PG8_BAR; PG8_MMA(0, 0, At, B0); PG8_MMA(0, 1, At, B1); PG8_BAR; PG8_SCHED;
.LBB0_847:
	s_waitcnt lgkmcnt(0)
	s_xor_b64 s[26:27], s[6:7], -1
	s_barrier
	v_mfma_f32_16x16x32_f16 v[58:61], v[146:149], v[186:189], v[58:61]
	s_setprio 1
	v_mfma_f32_16x16x32_f16 v[58:61], v[150:153], v[190:193], v[58:61]
	v_mfma_f32_16x16x32_f16 v[50:53], v[158:161], v[190:193], v[50:53]
	v_mfma_f32_16x16x32_f16 v[50:53], v[154:157], v[186:189], v[50:53]
	v_mfma_f32_16x16x32_f16 v[34:37], v[154:157], v[178:181], v[34:37]
	v_mfma_f32_16x16x32_f16 v[34:37], v[158:161], v[182:185], v[34:37]
	v_mfma_f32_16x16x32_f16 v[42:45], v[150:153], v[182:185], v[42:45]
	v_mfma_f32_16x16x32_f16 v[42:45], v[146:149], v[178:181], v[42:45]
	v_mfma_f32_16x16x32_f16 v[26:29], v[146:149], v[170:173], v[26:29]
	v_mfma_f32_16x16x32_f16 v[26:29], v[150:153], v[174:177], v[26:29]
	v_mfma_f32_16x16x32_f16 v[18:21], v[158:161], v[174:177], v[18:21]
	v_mfma_f32_16x16x32_f16 v[18:21], v[154:157], v[170:173], v[18:21]
	v_mfma_f32_16x16x32_f16 v[2:5], v[154:157], v[162:165], v[2:5]
	v_mfma_f32_16x16x32_f16 v[2:5], v[158:161], v[166:169], v[2:5]
	v_mfma_f32_16x16x32_f16 v[10:13], v[150:153], v[166:169], v[10:13]
	v_mfma_f32_16x16x32_f16 v[10:13], v[146:149], v[162:165], v[10:13]
	v_mfma_f32_16x16x32_f16 v[66:69], v[130:133], v[186:189], v[66:69]
	v_mfma_f32_16x16x32_f16 v[66:69], v[134:137], v[190:193], v[66:69]
	v_mfma_f32_16x16x32_f16 v[54:57], v[142:145], v[190:193], v[54:57]
	v_mfma_f32_16x16x32_f16 v[54:57], v[138:141], v[186:189], v[54:57]
	v_mfma_f32_16x16x32_f16 v[38:41], v[138:141], v[178:181], v[38:41]
	v_mfma_f32_16x16x32_f16 v[38:41], v[142:145], v[182:185], v[38:41]
	v_mfma_f32_16x16x32_f16 v[46:49], v[134:137], v[182:185], v[46:49]
	v_mfma_f32_16x16x32_f16 v[46:49], v[130:133], v[178:181], v[46:49]
	v_mfma_f32_16x16x32_f16 v[30:33], v[130:133], v[170:173], v[30:33]
	v_mfma_f32_16x16x32_f16 v[30:33], v[134:137], v[174:177], v[30:33]
	v_mfma_f32_16x16x32_f16 v[22:25], v[142:145], v[174:177], v[22:25]
	v_mfma_f32_16x16x32_f16 v[22:25], v[138:141], v[170:173], v[22:25]
	v_mfma_f32_16x16x32_f16 v[6:9], v[138:141], v[162:165], v[6:9]
	v_mfma_f32_16x16x32_f16 v[6:9], v[142:145], v[166:169], v[6:9]
	v_mfma_f32_16x16x32_f16 v[14:17], v[134:137], v[166:169], v[14:17]
	v_mfma_f32_16x16x32_f16 v[14:17], v[130:133], v[162:165], v[14:17]
	s_barrier
	s_setprio 0
	ds_read_b128 v[146:149], v213
	ds_read_b128 v[150:153], v213 offset:1024
	ds_read_b128 v[154:157], v213 offset:2048
	ds_read_b128 v[158:161], v213 offset:3072
	ds_read_b128 v[130:133], v214
	ds_read_b128 v[134:137], v214 offset:1024
	ds_read_b128 v[138:141], v214 offset:2048
	ds_read_b128 v[142:145], v214 offset:3072
	ds_read_b128 v[186:189], v212 offset:32768
	ds_read_b128 v[190:193], v212 offset:33792
	ds_read_b128 v[178:181], v212 offset:34816
	ds_read_b128 v[182:185], v212 offset:35840
	ds_read_b128 v[170:173], v212 offset:36864
	ds_read_b128 v[174:177], v212 offset:37888
	ds_read_b128 v[162:165], v212 offset:38912
	ds_read_b128 v[166:169], v212 offset:39936
	v_cndmask_b32_e64 v216, 0, 1, s[26:27]
	v_cmp_ne_u32_e64 s[6:7], 1, v216
	s_andn2_b64 vcc, exec, s[26:27]
	s_mov_b64 s[26:27], -1
	s_cbranch_vccnz .LBB0_849
	s_add_u32 s26, s24, 0x40000
	s_addc_u32 s27, s25, 0
	s_add_u32 m0, s14, 0x4000
	s_nop 0
	global_load_lds_dwordx4 v206, s[26:27]
	s_nop 0
	s_add_u32 m0, s14, 0x6000
	s_nop 0
	global_load_lds_dwordx4 v208, s[26:27]
	s_waitcnt vmcnt(8)
	s_mov_b64 s[26:27], 0

; #define PG8_STAGE(bufoff, gbase, voff) do { if constexpr (ABL & 1) break; glds16s<(bufoff)>((voff)[0], (const void*)(gbase), ldsbw); glds16s<(bufoff) + 8192>((voff)[1], (const void*)(gbase), ldsbw); } while (0)
; #define PG8_LDA(dst, b, h) do { if constexpr (ABL & 4) break; _Pragma("unroll") for (int m = 0; m < 4; ++m) _Pragma("unroll") for (int k = 0; k < 2; ++k) dst[m][k] = *(const LAS f16x8*)(lds + PG8_SA(b, h) + aoff + m * 2048 + k * 1024); } while (0)
; #define PG8_MMA(ai, bj, At, Bt) do { if constexpr (ABL & 2) break; __builtin_amdgcn_s_setprio(1); _Pragma("unroll") for (int m = 0; m < 4; ++m) _Pragma("unroll") for (int n = 0; n < 2; ++n) _Pragma("unroll") for (int k = 0; k < 2; ++k) \
;         acc[ai][bj][m][n] = __builtin_amdgcn_mfma_f32_16x16x32_f16(Bt[n][k], At[m][k], acc[ai][bj][m][n], 0, 0, 0); __builtin_amdgcn_s_setprio(0); } while (0)
; #define PG8_WAIT_V(n) asm volatile("s_waitcnt vmcnt(" #n ")" ::: "memory")
; #define PG8_WAIT_L(n) asm volatile("s_waitcnt lgkmcnt(" #n ")" ::: "memory")
; #define PG8_BAR __builtin_amdgcn_s_barrier()
; #define PG8_SCHED __builtin_amdgcn_sched_barrier(0)
;     ...
;             if (!fin) PG8_WAIT_V(8); else PG8_WAIT_V(0); PG8_WAIT_L(0); PG8_BAR; PG8_MMA(0, 0, At, B0); PG8_MMA(0, 1, At, B1); PG8_BAR; PG8_SCHED;
;             PG8_LDA(At, 1, 1); if (!fin) { PG8_STAGE(PG8_SB(1, 0), b3, voffB); PG8_STAGE(PG8_SB(1, 1), b3 + hstep, voffB); PG8_STAGE(PG8_SA(1, 0), a3, voffA); }
;             if (!fin) PG8_WAIT_V(8); PG8_WAIT_L(0); PG8_BAR; PG8_MMA(1, 0, At, B0); PG8_MMA(1, 1, At, B1); PG8_BAR; PG8_SCHED;
.LBB0_851:
	s_waitcnt lgkmcnt(0)
	s_barrier
	v_mfma_f32_16x16x32_f16 v[114:117], v[146:149], v[186:189], v[114:117]
	s_setprio 1
	v_mfma_f32_16x16x32_f16 v[114:117], v[150:153], v[190:193], v[114:117]
	v_mfma_f32_16x16x32_f16 v[110:113], v[158:161], v[190:193], v[110:113]
	v_mfma_f32_16x16x32_f16 v[110:113], v[154:157], v[186:189], v[110:113]
	v_mfma_f32_16x16x32_f16 v[98:101], v[154:157], v[178:181], v[98:101]
	v_mfma_f32_16x16x32_f16 v[98:101], v[158:161], v[182:185], v[98:101]
	v_mfma_f32_16x16x32_f16 v[106:109], v[150:153], v[182:185], v[106:109]
	v_mfma_f32_16x16x32_f16 v[106:109], v[146:149], v[178:181], v[106:109]
	v_mfma_f32_16x16x32_f16 v[90:93], v[146:149], v[170:173], v[90:93]
	v_mfma_f32_16x16x32_f16 v[90:93], v[150:153], v[174:177], v[90:93]
	v_mfma_f32_16x16x32_f16 v[82:85], v[158:161], v[174:177], v[82:85]
	v_mfma_f32_16x16x32_f16 v[82:85], v[154:157], v[170:173], v[82:85]
	v_mfma_f32_16x16x32_f16 v[62:65], v[154:157], v[162:165], v[62:65]
	v_mfma_f32_16x16x32_f16 v[62:65], v[158:161], v[166:169], v[62:65]
	v_mfma_f32_16x16x32_f16 v[74:77], v[150:153], v[166:169], v[74:77]
	v_mfma_f32_16x16x32_f16 v[74:77], v[146:149], v[162:165], v[74:77]
	v_mfma_f32_16x16x32_f16 v[126:129], v[130:133], v[186:189], v[126:129]
	v_mfma_f32_16x16x32_f16 v[126:129], v[134:137], v[190:193], v[126:129]
	v_mfma_f32_16x16x32_f16 v[122:125], v[142:145], v[190:193], v[122:125]
	v_mfma_f32_16x16x32_f16 v[122:125], v[138:141], v[186:189], v[122:125]
	v_mfma_f32_16x16x32_f16 v[102:105], v[138:141], v[178:181], v[102:105]
	v_mfma_f32_16x16x32_f16 v[102:105], v[142:145], v[182:185], v[102:105]
	v_mfma_f32_16x16x32_f16 v[118:121], v[134:137], v[182:185], v[118:121]
	v_mfma_f32_16x16x32_f16 v[118:121], v[130:133], v[178:181], v[118:121]
	v_mfma_f32_16x16x32_f16 v[94:97], v[130:133], v[170:173], v[94:97]
	v_mfma_f32_16x16x32_f16 v[94:97], v[134:137], v[174:177], v[94:97]
	v_mfma_f32_16x16x32_f16 v[86:89], v[142:145], v[174:177], v[86:89]
	v_mfma_f32_16x16x32_f16 v[86:89], v[138:141], v[170:173], v[86:89]
	v_mfma_f32_16x16x32_f16 v[70:73], v[138:141], v[162:165], v[70:73]
	v_mfma_f32_16x16x32_f16 v[70:73], v[142:145], v[166:169], v[70:73]
	v_mfma_f32_16x16x32_f16 v[78:81], v[134:137], v[166:169], v[78:81]
	v_mfma_f32_16x16x32_f16 v[78:81], v[130:133], v[162:165], v[78:81]
	s_barrier
	s_setprio 0
	ds_read_b128 v[186:189], v212 offset:49152
	ds_read_b128 v[190:193], v212 offset:50176
	ds_read_b128 v[178:181], v212 offset:51200
	ds_read_b128 v[182:185], v212 offset:52224
	ds_read_b128 v[170:173], v212 offset:53248
	ds_read_b128 v[174:177], v212 offset:54272
	ds_read_b128 v[162:165], v212 offset:55296
	ds_read_b128 v[166:169], v212 offset:56320
	s_and_b64 vcc, exec, s[6:7]
	s_cbranch_vccnz .LBB0_842
	s_add_u32 s6, s24, 0x80
	s_addc_u32 s7, s25, 0
	s_add_u32 s24, s8, 0x80
	s_addc_u32 s25, s9, 0
	s_add_u32 m0, s14, 0x18000
	s_nop 0
	global_load_lds_dwordx4 v207, s[24:25]
	s_nop 0
	s_add_u32 m0, s14, 0x1a000
	s_nop 0
	global_load_lds_dwordx4 v209, s[24:25]
	s_add_u32 s8, s8, 0x40080
	s_addc_u32 s9, s9, 0
	s_add_u32 m0, s14, 0x1c000
	s_nop 0
	global_load_lds_dwordx4 v207, s[8:9]
	s_nop 0
	s_add_u32 m0, s14, 0x1e000
	s_nop 0
	global_load_lds_dwordx4 v209, s[8:9]
	s_nop 0
	s_add_u32 m0, s14, 0x8000
	s_nop 0
	global_load_lds_dwordx4 v206, s[6:7]
	s_nop 0
	s_add_u32 m0, s14, 0xa000
	s_nop 0
	global_load_lds_dwordx4 v208, s[6:7]
	s_waitcnt vmcnt(8)
	s_branch .LBB0_842

; #define PG8_STAGE(bufoff, gbase, voff) do { if constexpr (ABL & 1) break; glds16s<(bufoff)>((voff)[0], (const void*)(gbase), ldsbw); glds16s<(bufoff) + 8192>((voff)[1], (const void*)(gbase), ldsbw); } while (0)
; #define PG8_LDA(dst, b, h) do { if constexpr (ABL & 4) break; _Pragma("unroll") for (int m = 0; m < 4; ++m) _Pragma("unroll") for (int k = 0; k < 2; ++k) dst[m][k] = *(const LAS f16x8*)(lds + PG8_SA(b, h) + aoff + m * 2048 + k * 1024); } while (0)
; #define PG8_LDB(dst, b, h) do { if constexpr (ABL & 4) break; _Pragma("unroll") for (int n = 0; n < 2; ++n) _Pragma("unroll") for (int k = 0; k < 2; ++k) dst[n][k] = *(const LAS f16x8*)(lds + PG8_SB(b, h) + boff + n * 2048 + k * 1024); } while (0)
; #define PG8_BAR __builtin_amdgcn_s_barrier()
;     ...
;         for (int t = 0; t < nt; t += 2) {
;             const bool last = (t == nt - 2);
;             const char* a1 = cA + (size_t)(t + 1) * kstep;
;             const char* a2 = last ? nA : cA + (size_t)(t + 2) * kstep; const char* b2 = last ? nB : cB + (size_t)(t + 2) * kstep;
;             const char* a3 = a2 + kstep; const char* b3 = b2 + kstep;
;             if (last && has_next) S.a_ready(nxt);
;             if constexpr (SP2) {
;             PG8_LDB(B0, 0, 0); PG8_LDB(B1, 0, 1); PG8_SCHED; PG8_LDA(At, 0, 0); PG8_STAGE(PG8_SA(1, 1), a1 + hstep, voffA);
;             PG8_WAIT_V(8); PG8_WAIT_L(0); PG8_BAR; PG8_MMAF(0, 0, At, B0); PG8_MMAF(0, 1, At, B1); PG8_BAR; PG8_SCHED;
;             const bool fin = last && !has_next;
;             PG8_LDA(At, 0, 1); if (!fin) { PG8_STAGE(PG8_SB(0, 0), b2, voffB); PG8_STAGE(PG8_SB(0, 1), b2 + hstep, voffB); PG8_STAGE(PG8_SA(0, 0), a2, voffA); }
;             if (!fin) PG8_WAIT_V(8); else PG8_WAIT_V(2); PG8_WAIT_L(0); PG8_BAR; PG8_MMAF(1, 0, At, B0); PG8_MMAF(1, 1, At, B1); PG8_BAR; PG8_SCHED;
;             PG8_LDB(B0, 1, 0); PG8_LDB(B1, 1, 1); PG8_SCHED; PG8_LDA(At, 1, 0); if (!fin) PG8_STAGE(PG8_SA(0, 1), a2 + hstep, voffA);
;             if (!fin) PG8_WAIT_V(8); else PG8_WAIT_V(0); PG8_WAIT_L(0); PG8_BAR; PG8_MMA(0, 0, At, B0); PG8_MMA(0, 1, At, B1); PG8_BAR; PG8_SCHED;
;             PG8_LDA(At, 1, 1); if (!fin) { PG8_STAGE(PG8_SB(1, 0), b3, voffB); PG8_STAGE(PG8_SB(1, 1), b3 + hstep, voffB); PG8_STAGE(PG8_SA(1, 0), a3, voffA); }
;             if (!fin) PG8_WAIT_V(8); PG8_WAIT_L(0); PG8_BAR; PG8_MMA(1, 0, At, B0); PG8_MMA(1, 1, At, B1); PG8_BAR; PG8_SCHED;
.LBB0_988:
	s_waitcnt lgkmcnt(0)
	s_barrier
	v_mfma_f32_16x16x32_f16 v[62:65], v[166:169], v[186:189], v[62:65]
	s_setprio 1
	v_mfma_f32_16x16x32_f16 v[62:65], v[170:173], v[190:193], v[62:65]
	v_mfma_f32_16x16x32_f16 v[58:61], v[162:165], v[190:193], v[58:61]
	v_mfma_f32_16x16x32_f16 v[58:61], v[158:161], v[186:189], v[58:61]
	v_mfma_f32_16x16x32_f16 v[42:45], v[158:161], v[178:181], v[42:45]
	v_mfma_f32_16x16x32_f16 v[42:45], v[162:165], v[182:185], v[42:45]
	v_mfma_f32_16x16x32_f16 v[46:49], v[170:173], v[182:185], v[46:49]
	v_mfma_f32_16x16x32_f16 v[46:49], v[166:169], v[178:181], v[46:49]
	v_mfma_f32_16x16x32_f16 v[30:33], v[166:169], v[138:141], v[30:33]
	v_mfma_f32_16x16x32_f16 v[30:33], v[170:173], v[174:177], v[30:33]
	v_mfma_f32_16x16x32_f16 v[26:29], v[162:165], v[174:177], v[26:29]
	v_mfma_f32_16x16x32_f16 v[26:29], v[158:161], v[138:141], v[26:29]
	v_mfma_f32_16x16x32_f16 v[10:13], v[158:161], v[114:117], v[10:13]
	v_mfma_f32_16x16x32_f16 v[10:13], v[162:165], v[126:129], v[10:13]
	v_mfma_f32_16x16x32_f16 v[14:17], v[170:173], v[126:129], v[14:17]
	v_mfma_f32_16x16x32_f16 v[14:17], v[166:169], v[114:117], v[14:17]
	v_mfma_f32_16x16x32_f16 v[54:57], v[90:93], v[186:189], v[54:57]
	v_mfma_f32_16x16x32_f16 v[54:57], v[102:105], v[190:193], v[54:57]
	v_mfma_f32_16x16x32_f16 v[50:53], v[78:81], v[190:193], v[50:53]
	v_mfma_f32_16x16x32_f16 v[50:53], v[66:69], v[186:189], v[50:53]
	v_mfma_f32_16x16x32_f16 v[34:37], v[66:69], v[178:181], v[34:37]
	v_mfma_f32_16x16x32_f16 v[34:37], v[78:81], v[182:185], v[34:37]
	v_mfma_f32_16x16x32_f16 v[38:41], v[102:105], v[182:185], v[38:41]
	v_mfma_f32_16x16x32_f16 v[38:41], v[90:93], v[178:181], v[38:41]
	v_mfma_f32_16x16x32_f16 v[22:25], v[90:93], v[138:141], v[22:25]
	v_mfma_f32_16x16x32_f16 v[22:25], v[102:105], v[174:177], v[22:25]
	v_mfma_f32_16x16x32_f16 v[18:21], v[78:81], v[174:177], v[18:21]
	v_mfma_f32_16x16x32_f16 v[18:21], v[66:69], v[138:141], v[18:21]
	v_mfma_f32_16x16x32_f16 v[2:5], v[66:69], v[114:117], v[2:5]
	v_mfma_f32_16x16x32_f16 v[2:5], v[78:81], v[126:129], v[2:5]
	v_mfma_f32_16x16x32_f16 v[6:9], v[102:105], v[126:129], v[6:9]
	v_mfma_f32_16x16x32_f16 v[6:9], v[90:93], v[114:117], v[6:9]
	s_barrier
	s_setprio 0
	s_add_i32 s54, s54, 2
	s_add_u32 s52, s52, 0x100
	s_addc_u32 s53, s53, 0
	s_cmp_gt_u32 s54, 41
	s_cbranch_scc1 .LBB0_999

; #define PG8_STAGE(bufoff, gbase, voff) do { if constexpr (ABL & 1) break; glds16s<(bufoff)>((voff)[0], (const void*)(gbase), ldsbw); glds16s<(bufoff) + 8192>((voff)[1], (const void*)(gbase), ldsbw); } while (0)
; #define PG8_LDA(dst, b, h) do { if constexpr (ABL & 4) break; _Pragma("unroll") for (int m = 0; m < 4; ++m) _Pragma("unroll") for (int k = 0; k < 2; ++k) dst[m][k] = *(const LAS f16x8*)(lds + PG8_SA(b, h) + aoff + m * 2048 + k * 1024); } while (0)
; #define PG8_LDB(dst, b, h) do { if constexpr (ABL & 4) break; _Pragma("unroll") for (int n = 0; n < 2; ++n) _Pragma("unroll") for (int k = 0; k < 2; ++k) dst[n][k] = *(const LAS f16x8*)(lds + PG8_SB(b, h) + boff + n * 2048 + k * 1024); } while (0)
; #define PG8_MMA(ai, bj, At, Bt) do { if constexpr (ABL & 2) break; __builtin_amdgcn_s_setprio(1); _Pragma("unroll") for (int m = 0; m < 4; ++m) _Pragma("unroll") for (int n = 0; n < 2; ++n) _Pragma("unroll") for (int k = 0; k < 2; ++k) \
;         acc[ai][bj][m][n] = __builtin_amdgcn_mfma_f32_16x16x32_f16(Bt[n][k], At[m][k], acc[ai][bj][m][n], 0, 0, 0); __builtin_amdgcn_s_setprio(0); } while (0)
; #define PG8_MMAF(ai, bj, At, Bt) do { if (t == 0) PG8_MMA0(ai, bj, At, Bt); else PG8_MMA(ai, bj, At, Bt); } while (0)
; #define PG8_WAIT_V(n) asm volatile("s_waitcnt vmcnt(" #n ")" ::: "memory")
; #define PG8_WAIT_L(n) asm volatile("s_waitcnt lgkmcnt(" #n ")" ::: "memory")
; #define PG8_BAR __builtin_amdgcn_s_barrier()
; #define PG8_SCHED __builtin_amdgcn_sched_barrier(0)
;     ...
;             if (!fin) PG8_WAIT_V(8); else PG8_WAIT_V(2); PG8_WAIT_L(0); PG8_BAR; PG8_MMAF(1, 0, At, B0); PG8_MMAF(1, 1, At, B1); PG8_BAR; PG8_SCHED;
;             PG8_LDB(B0, 1, 0); PG8_LDB(B1, 1, 1); PG8_SCHED; PG8_LDA(At, 1, 0); if (!fin) PG8_STAGE(PG8_SA(0, 1), a2 + hstep, voffA);
;             if (!fin) PG8_WAIT_V(8); else PG8_WAIT_V(0); PG8_WAIT_L(0); PG8_BAR; PG8_MMA(0, 0, At, B0); PG8_MMA(0, 1, At, B1); PG8_BAR; PG8_SCHED;
.LBB0_993:
	s_waitcnt lgkmcnt(0)
	s_xor_b64 s[26:27], s[6:7], -1
	s_barrier
	v_mfma_f32_16x16x32_f16 v[62:65], v[158:161], v[186:189], v[62:65]
	s_setprio 1
	v_mfma_f32_16x16x32_f16 v[62:65], v[162:165], v[190:193], v[62:65]
	v_mfma_f32_16x16x32_f16 v[58:61], v[170:173], v[190:193], v[58:61]
	v_mfma_f32_16x16x32_f16 v[58:61], v[166:169], v[186:189], v[58:61]
	v_mfma_f32_16x16x32_f16 v[42:45], v[166:169], v[178:181], v[42:45]
	v_mfma_f32_16x16x32_f16 v[42:45], v[170:173], v[182:185], v[42:45]
	v_mfma_f32_16x16x32_f16 v[46:49], v[162:165], v[182:185], v[46:49]
	v_mfma_f32_16x16x32_f16 v[46:49], v[158:161], v[178:181], v[46:49]
	v_mfma_f32_16x16x32_f16 v[30:33], v[158:161], v[154:157], v[30:33]
	v_mfma_f32_16x16x32_f16 v[30:33], v[162:165], v[174:177], v[30:33]
	v_mfma_f32_16x16x32_f16 v[26:29], v[170:173], v[174:177], v[26:29]
	v_mfma_f32_16x16x32_f16 v[26:29], v[166:169], v[154:157], v[26:29]
	v_mfma_f32_16x16x32_f16 v[10:13], v[166:169], v[146:149], v[10:13]
	v_mfma_f32_16x16x32_f16 v[10:13], v[170:173], v[150:153], v[10:13]
	v_mfma_f32_16x16x32_f16 v[14:17], v[162:165], v[150:153], v[14:17]
	v_mfma_f32_16x16x32_f16 v[14:17], v[158:161], v[146:149], v[14:17]
	v_mfma_f32_16x16x32_f16 v[54:57], v[66:69], v[186:189], v[54:57]
	v_mfma_f32_16x16x32_f16 v[54:57], v[78:81], v[190:193], v[54:57]
	v_mfma_f32_16x16x32_f16 v[50:53], v[102:105], v[190:193], v[50:53]
	v_mfma_f32_16x16x32_f16 v[50:53], v[90:93], v[186:189], v[50:53]
	v_mfma_f32_16x16x32_f16 v[34:37], v[90:93], v[178:181], v[34:37]
	v_mfma_f32_16x16x32_f16 v[34:37], v[102:105], v[182:185], v[34:37]
	v_mfma_f32_16x16x32_f16 v[38:41], v[78:81], v[182:185], v[38:41]
	v_mfma_f32_16x16x32_f16 v[38:41], v[66:69], v[178:181], v[38:41]
	v_mfma_f32_16x16x32_f16 v[22:25], v[66:69], v[154:157], v[22:25]
	v_mfma_f32_16x16x32_f16 v[22:25], v[78:81], v[174:177], v[22:25]
	v_mfma_f32_16x16x32_f16 v[18:21], v[102:105], v[174:177], v[18:21]
	v_mfma_f32_16x16x32_f16 v[18:21], v[90:93], v[154:157], v[18:21]
	v_mfma_f32_16x16x32_f16 v[2:5], v[90:93], v[146:149], v[2:5]
	v_mfma_f32_16x16x32_f16 v[2:5], v[102:105], v[150:153], v[2:5]
	v_mfma_f32_16x16x32_f16 v[6:9], v[78:81], v[150:153], v[6:9]
	v_mfma_f32_16x16x32_f16 v[6:9], v[66:69], v[146:149], v[6:9]
	s_barrier
	s_setprio 0
	ds_read_b128 v[166:169], v216
	ds_read_b128 v[170:173], v216 offset:1024
	ds_read_b128 v[158:161], v216 offset:2048
	ds_read_b128 v[162:165], v216 offset:3072
	ds_read_b128 v[90:93], v217
	ds_read_b128 v[102:105], v217 offset:1024
	ds_read_b128 v[66:69], v217 offset:2048
	ds_read_b128 v[78:81], v217 offset:3072
	ds_read_b128 v[198:201], v215 offset:32768
	ds_read_b128 v[202:205], v215 offset:33792
	ds_read_b128 v[190:193], v215 offset:34816
	ds_read_b128 v[194:197], v215 offset:35840
	ds_read_b128 v[182:185], v215 offset:36864
	ds_read_b128 v[186:189], v215 offset:37888
	ds_read_b128 v[174:177], v215 offset:38912
	ds_read_b128 v[178:181], v215 offset:39936
	v_cndmask_b32_e64 v146, 0, 1, s[26:27]
	v_cmp_ne_u32_e64 s[6:7], 1, v146
	s_andn2_b64 vcc, exec, s[26:27]
	s_mov_b64 s[26:27], -1
	s_cbranch_vccnz .LBB0_995
	s_add_u32 s26, s24, 0xb0000
	s_addc_u32 s27, s25, 0
	s_add_u32 m0, s28, 0x4000
	s_nop 0
	global_load_lds_dwordx4 v1, s[26:27]
	s_nop 0
	s_add_u32 m0, s28, 0x6000
	s_nop 0
	global_load_lds_dwordx4 v211, s[26:27]
	s_waitcnt vmcnt(8)
	s_mov_b64 s[26:27], 0

; #define PG8_STAGE(bufoff, gbase, voff) do { if constexpr (ABL & 1) break; glds16s<(bufoff)>((voff)[0], (const void*)(gbase), ldsbw); glds16s<(bufoff) + 8192>((voff)[1], (const void*)(gbase), ldsbw); } while (0)
; #define PG8_LDA(dst, b, h) do { if constexpr (ABL & 4) break; _Pragma("unroll") for (int m = 0; m < 4; ++m) _Pragma("unroll") for (int k = 0; k < 2; ++k) dst[m][k] = *(const LAS f16x8*)(lds + PG8_SA(b, h) + aoff + m * 2048 + k * 1024); } while (0)
; #define PG8_LDB(dst, b, h) do { if constexpr (ABL & 4) break; _Pragma("unroll") for (int n = 0; n < 2; ++n) _Pragma("unroll") for (int k = 0; k < 2; ++k) dst[n][k] = *(const LAS f16x8*)(lds + PG8_SB(b, h) + boff + n * 2048 + k * 1024); } while (0)
; #define PG8_BAR __builtin_amdgcn_s_barrier()
;     ...
;         for (int t = 0; t < nt; t += 2) {
;             const bool last = (t == nt - 2);
;             const char* a1 = cA + (size_t)(t + 1) * kstep;
;             const char* a2 = last ? nA : cA + (size_t)(t + 2) * kstep; const char* b2 = last ? nB : cB + (size_t)(t + 2) * kstep;
;             const char* a3 = a2 + kstep; const char* b3 = b2 + kstep;
;             if (last && has_next) S.a_ready(nxt);
;             if constexpr (SP2) {
;             PG8_LDB(B0, 0, 0); PG8_LDB(B1, 0, 1); PG8_SCHED; PG8_LDA(At, 0, 0); PG8_STAGE(PG8_SA(1, 1), a1 + hstep, voffA);
;             PG8_WAIT_V(8); PG8_WAIT_L(0); PG8_BAR; PG8_MMAF(0, 0, At, B0); PG8_MMAF(0, 1, At, B1); PG8_BAR; PG8_SCHED;
;             const bool fin = last && !has_next;
;             PG8_LDA(At, 0, 1); if (!fin) { PG8_STAGE(PG8_SB(0, 0), b2, voffB); PG8_STAGE(PG8_SB(0, 1), b2 + hstep, voffB); PG8_STAGE(PG8_SA(0, 0), a2, voffA); }
;             if (!fin) PG8_WAIT_V(8); else PG8_WAIT_V(2); PG8_WAIT_L(0); PG8_BAR; PG8_MMAF(1, 0, At, B0); PG8_MMAF(1, 1, At, B1); PG8_BAR; PG8_SCHED;
;             PG8_LDB(B0, 1, 0); PG8_LDB(B1, 1, 1); PG8_SCHED; PG8_LDA(At, 1, 0); if (!fin) PG8_STAGE(PG8_SA(0, 1), a2 + hstep, voffA);
;             if (!fin) PG8_WAIT_V(8); else PG8_WAIT_V(0); PG8_WAIT_L(0); PG8_BAR; PG8_MMA(0, 0, At, B0); PG8_MMA(0, 1, At, B1); PG8_BAR; PG8_SCHED;
;             PG8_LDA(At, 1, 1); if (!fin) { PG8_STAGE(PG8_SB(1, 0), b3, voffB); PG8_STAGE(PG8_SB(1, 1), b3 + hstep, voffB); PG8_STAGE(PG8_SA(1, 0), a3, voffA); }
;             if (!fin) PG8_WAIT_V(8); PG8_WAIT_L(0); PG8_BAR; PG8_MMA(1, 0, At, B0); PG8_MMA(1, 1, At, B1); PG8_BAR; PG8_SCHED;
.LBB0_1112:
	s_waitcnt lgkmcnt(0)
	s_barrier
	v_mfma_f32_16x16x32_f16 v[62:65], v[146:149], v[186:189], v[62:65]
	s_setprio 1
	v_mfma_f32_16x16x32_f16 v[62:65], v[150:153], v[190:193], v[62:65]
	v_mfma_f32_16x16x32_f16 v[58:61], v[158:161], v[190:193], v[58:61]
	v_mfma_f32_16x16x32_f16 v[58:61], v[154:157], v[186:189], v[58:61]
	v_mfma_f32_16x16x32_f16 v[42:45], v[154:157], v[178:181], v[42:45]
	v_mfma_f32_16x16x32_f16 v[42:45], v[158:161], v[182:185], v[42:45]
	v_mfma_f32_16x16x32_f16 v[46:49], v[150:153], v[182:185], v[46:49]
	v_mfma_f32_16x16x32_f16 v[46:49], v[146:149], v[178:181], v[46:49]
	v_mfma_f32_16x16x32_f16 v[30:33], v[146:149], v[170:173], v[30:33]
	v_mfma_f32_16x16x32_f16 v[30:33], v[150:153], v[174:177], v[30:33]
	v_mfma_f32_16x16x32_f16 v[26:29], v[158:161], v[174:177], v[26:29]
	v_mfma_f32_16x16x32_f16 v[26:29], v[154:157], v[170:173], v[26:29]
	v_mfma_f32_16x16x32_f16 v[10:13], v[154:157], v[162:165], v[10:13]
	v_mfma_f32_16x16x32_f16 v[10:13], v[158:161], v[166:169], v[10:13]
	v_mfma_f32_16x16x32_f16 v[14:17], v[150:153], v[166:169], v[14:17]
	v_mfma_f32_16x16x32_f16 v[14:17], v[146:149], v[162:165], v[14:17]
	v_mfma_f32_16x16x32_f16 v[54:57], v[130:133], v[186:189], v[54:57]
	v_mfma_f32_16x16x32_f16 v[54:57], v[134:137], v[190:193], v[54:57]
	v_mfma_f32_16x16x32_f16 v[50:53], v[142:145], v[190:193], v[50:53]
	v_mfma_f32_16x16x32_f16 v[50:53], v[138:141], v[186:189], v[50:53]
	v_mfma_f32_16x16x32_f16 v[34:37], v[138:141], v[178:181], v[34:37]
	v_mfma_f32_16x16x32_f16 v[34:37], v[142:145], v[182:185], v[34:37]
	v_mfma_f32_16x16x32_f16 v[38:41], v[134:137], v[182:185], v[38:41]
	v_mfma_f32_16x16x32_f16 v[38:41], v[130:133], v[178:181], v[38:41]
	v_mfma_f32_16x16x32_f16 v[22:25], v[130:133], v[170:173], v[22:25]
	v_mfma_f32_16x16x32_f16 v[22:25], v[134:137], v[174:177], v[22:25]
	v_mfma_f32_16x16x32_f16 v[18:21], v[142:145], v[174:177], v[18:21]
	v_mfma_f32_16x16x32_f16 v[18:21], v[138:141], v[170:173], v[18:21]
	v_mfma_f32_16x16x32_f16 v[2:5], v[138:141], v[162:165], v[2:5]
	v_mfma_f32_16x16x32_f16 v[2:5], v[142:145], v[166:169], v[2:5]
	v_mfma_f32_16x16x32_f16 v[6:9], v[134:137], v[166:169], v[6:9]
	v_mfma_f32_16x16x32_f16 v[6:9], v[130:133], v[162:165], v[6:9]
	s_barrier
	s_setprio 0
	s_add_i32 s58, s58, 2
	s_add_u32 s54, s54, 0x100
	s_addc_u32 s55, s55, 0
	s_cmp_gt_u32 s58, 13
	s_cbranch_scc1 .LBB0_1123
.LBB0_1113:
	ds_read_b128 v[146:149], v201
	ds_read_b128 v[150:153], v201 offset:1024
	ds_read_b128 v[154:157], v201 offset:2048
	ds_read_b128 v[158:161], v201 offset:3072
	ds_read_b128 v[130:133], v202
	ds_read_b128 v[134:137], v202 offset:1024
	ds_read_b128 v[138:141], v202 offset:2048
	ds_read_b128 v[142:145], v202 offset:3072
	s_mov_b64 s[6:7], s[52:53]
	s_add_u32 s52, s6, 0x100
	s_addc_u32 s53, s7, 0
	s_cmp_eq_u32 s58, 12
	s_cselect_b64 s[26:27], -1, 0
	s_and_b64 s[8:9], s[26:27], exec
	s_cselect_b32 s25, s43, s53
	s_cselect_b32 s24, s56, s52
	s_cselect_b32 s9, s41, s55
	s_cselect_b32 s8, s57, s54
	ds_read_b128 v[162:165], v203
	ds_read_b128 v[166:169], v203 offset:1024
	ds_read_b128 v[170:173], v203 offset:2048
	ds_read_b128 v[174:177], v203 offset:3072
	ds_read_b128 v[178:181], v203 offset:4096
	ds_read_b128 v[182:185], v203 offset:5120
	ds_read_b128 v[186:189], v203 offset:6144
	ds_read_b128 v[190:193], v203 offset:7168
	s_add_u32 s6, s6, 0x40080
	s_addc_u32 s7, s7, 0
	s_add_u32 m0, s28, 0xc000
	s_nop 0
	global_load_lds_dwordx4 v1, s[6:7]
	s_nop 0
	s_add_u32 m0, s28, 0xe000
	s_nop 0
	global_load_lds_dwordx4 v199, s[6:7]
	s_waitcnt vmcnt(8)
	s_waitcnt lgkmcnt(0)
	s_barrier
	v_mfma_f32_16x16x32_f16 v[126:129], v[146:149], v[162:165], v[126:129]
	s_setprio 1
	v_mfma_f32_16x16x32_f16 v[126:129], v[150:153], v[166:169], v[126:129]
	v_mfma_f32_16x16x32_f16 v[122:125], v[158:161], v[166:169], v[122:125]
	v_mfma_f32_16x16x32_f16 v[122:125], v[154:157], v[162:165], v[122:125]
	v_mfma_f32_16x16x32_f16 v[106:109], v[154:157], v[170:173], v[106:109]
	v_mfma_f32_16x16x32_f16 v[106:109], v[158:161], v[174:177], v[106:109]
	v_mfma_f32_16x16x32_f16 v[110:113], v[150:153], v[174:177], v[110:113]
	v_mfma_f32_16x16x32_f16 v[110:113], v[146:149], v[170:173], v[110:113]
	v_mfma_f32_16x16x32_f16 v[94:97], v[146:149], v[178:181], v[94:97]
	v_mfma_f32_16x16x32_f16 v[94:97], v[150:153], v[182:185], v[94:97]
	v_mfma_f32_16x16x32_f16 v[90:93], v[158:161], v[182:185], v[90:93]
	v_mfma_f32_16x16x32_f16 v[90:93], v[154:157], v[178:181], v[90:93]
	v_mfma_f32_16x16x32_f16 v[74:77], v[154:157], v[186:189], v[74:77]
	v_mfma_f32_16x16x32_f16 v[74:77], v[158:161], v[190:193], v[74:77]
	v_mfma_f32_16x16x32_f16 v[78:81], v[150:153], v[190:193], v[78:81]
	v_mfma_f32_16x16x32_f16 v[78:81], v[146:149], v[186:189], v[78:81]
	v_mfma_f32_16x16x32_f16 v[118:121], v[130:133], v[162:165], v[118:121]
	v_mfma_f32_16x16x32_f16 v[118:121], v[134:137], v[166:169], v[118:121]
	v_mfma_f32_16x16x32_f16 v[114:117], v[142:145], v[166:169], v[114:117]
	v_mfma_f32_16x16x32_f16 v[114:117], v[138:141], v[162:165], v[114:117]
	v_mfma_f32_16x16x32_f16 v[98:101], v[138:141], v[170:173], v[98:101]
	v_mfma_f32_16x16x32_f16 v[98:101], v[142:145], v[174:177], v[98:101]
	v_mfma_f32_16x16x32_f16 v[102:105], v[134:137], v[174:177], v[102:105]
	v_mfma_f32_16x16x32_f16 v[102:105], v[130:133], v[170:173], v[102:105]
	v_mfma_f32_16x16x32_f16 v[86:89], v[130:133], v[178:181], v[86:89]
	v_mfma_f32_16x16x32_f16 v[86:89], v[134:137], v[182:185], v[86:89]
	v_mfma_f32_16x16x32_f16 v[82:85], v[142:145], v[182:185], v[82:85]
	v_mfma_f32_16x16x32_f16 v[82:85], v[138:141], v[178:181], v[82:85]
	v_mfma_f32_16x16x32_f16 v[66:69], v[138:141], v[186:189], v[66:69]
	v_mfma_f32_16x16x32_f16 v[66:69], v[142:145], v[190:193], v[66:69]
	v_mfma_f32_16x16x32_f16 v[70:73], v[134:137], v[190:193], v[70:73]
	v_mfma_f32_16x16x32_f16 v[70:73], v[130:133], v[186:189], v[70:73]
	s_barrier
	s_setprio 0
	ds_read_b128 v[186:189], v203 offset:16384
	ds_read_b128 v[190:193], v203 offset:17408
	ds_read_b128 v[178:181], v203 offset:18432
	ds_read_b128 v[182:185], v203 offset:19456
	ds_read_b128 v[170:173], v203 offset:20480
	ds_read_b128 v[174:177], v203 offset:21504
	ds_read_b128 v[162:165], v203 offset:22528
	ds_read_b128 v[166:169], v203 offset:23552
	s_and_b64 s[6:7], s[4:5], s[26:27]
	s_mov_b64 s[26:27], -1
	s_and_b64 vcc, exec, s[6:7]
	s_cbranch_vccnz .LBB0_1115
	s_add_u32 m0, s28, 0x10000
	s_nop 0
	global_load_lds_dwordx4 v198, s[8:9]
	s_nop 0
	s_add_u32 m0, s28, 0x12000
	s_nop 0
	global_load_lds_dwordx4 v200, s[8:9]
	s_add_u32 s26, s8, 0x40000
	s_addc_u32 s27, s9, 0
	s_add_u32 m0, s28, 0x14000
	s_nop 0
	global_load_lds_dwordx4 v198, s[26:27]
	s_nop 0
	s_add_u32 m0, s28, 0x16000
	s_nop 0
	global_load_lds_dwordx4 v200, s[26:27]
	s_mov_b64 s[26:27], 0
	s_add_u32 m0, s28, 0
	s_nop 0
	global_load_lds_dwordx4 v1, s[24:25]
	s_nop 0
	s_add_u32 m0, s28, 0x2000
	s_nop 0
	global_load_lds_dwordx4 v199, s[24:25]
	s_waitcnt vmcnt(8)

; #define PG8_STAGE(bufoff, gbase, voff) do { if constexpr (ABL & 1) break; glds16s<(bufoff)>((voff)[0], (const void*)(gbase), ldsbw); glds16s<(bufoff) + 8192>((voff)[1], (const void*)(gbase), ldsbw); } while (0)
; #define PG8_LDA(dst, b, h) do { if constexpr (ABL & 4) break; _Pragma("unroll") for (int m = 0; m < 4; ++m) _Pragma("unroll") for (int k = 0; k < 2; ++k) dst[m][k] = *(const LAS f16x8*)(lds + PG8_SA(b, h) + aoff + m * 2048 + k * 1024); } while (0)
; #define PG8_LDB(dst, b, h) do { if constexpr (ABL & 4) break; _Pragma("unroll") for (int n = 0; n < 2; ++n) _Pragma("unroll") for (int k = 0; k < 2; ++k) dst[n][k] = *(const LAS f16x8*)(lds + PG8_SB(b, h) + boff + n * 2048 + k * 1024); } while (0)
; #define PG8_MMA(ai, bj, At, Bt) do { if constexpr (ABL & 2) break; __builtin_amdgcn_s_setprio(1); _Pragma("unroll") for (int m = 0; m < 4; ++m) _Pragma("unroll") for (int n = 0; n < 2; ++n) _Pragma("unroll") for (int k = 0; k < 2; ++k) \
;         acc[ai][bj][m][n] = __builtin_amdgcn_mfma_f32_16x16x32_f16(Bt[n][k], At[m][k], acc[ai][bj][m][n], 0, 0, 0); __builtin_amdgcn_s_setprio(0); } while (0)
; #define PG8_MMAF(ai, bj, At, Bt) do { if (t == 0) PG8_MMA0(ai, bj, At, Bt); else PG8_MMA(ai, bj, At, Bt); } while (0)
; #define PG8_WAIT_V(n) asm volatile("s_waitcnt vmcnt(" #n ")" ::: "memory")
; #define PG8_WAIT_L(n) asm volatile("s_waitcnt lgkmcnt(" #n ")" ::: "memory")
; #define PG8_BAR __builtin_amdgcn_s_barrier()
; #define PG8_SCHED __builtin_amdgcn_sched_barrier(0)
;     ...
;             if (!fin) PG8_WAIT_V(8); else PG8_WAIT_V(2); PG8_WAIT_L(0); PG8_BAR; PG8_MMAF(1, 0, At, B0); PG8_MMAF(1, 1, At, B1); PG8_BAR; PG8_SCHED;
;             PG8_LDB(B0, 1, 0); PG8_LDB(B1, 1, 1); PG8_SCHED; PG8_LDA(At, 1, 0); if (!fin) PG8_STAGE(PG8_SA(0, 1), a2 + hstep, voffA);
;             if (!fin) PG8_WAIT_V(8); else PG8_WAIT_V(0); PG8_WAIT_L(0); PG8_BAR; PG8_MMA(0, 0, At, B0); PG8_MMA(0, 1, At, B1); PG8_BAR; PG8_SCHED;
.LBB0_1117:
	s_waitcnt lgkmcnt(0)
	s_xor_b64 s[26:27], s[6:7], -1
	s_barrier
	v_mfma_f32_16x16x32_f16 v[62:65], v[146:149], v[186:189], v[62:65]
	s_setprio 1
	v_mfma_f32_16x16x32_f16 v[62:65], v[150:153], v[190:193], v[62:65]
	v_mfma_f32_16x16x32_f16 v[58:61], v[158:161], v[190:193], v[58:61]
	v_mfma_f32_16x16x32_f16 v[58:61], v[154:157], v[186:189], v[58:61]
	v_mfma_f32_16x16x32_f16 v[42:45], v[154:157], v[178:181], v[42:45]
	v_mfma_f32_16x16x32_f16 v[42:45], v[158:161], v[182:185], v[42:45]
	v_mfma_f32_16x16x32_f16 v[46:49], v[150:153], v[182:185], v[46:49]
	v_mfma_f32_16x16x32_f16 v[46:49], v[146:149], v[178:181], v[46:49]
	v_mfma_f32_16x16x32_f16 v[30:33], v[146:149], v[170:173], v[30:33]
	v_mfma_f32_16x16x32_f16 v[30:33], v[150:153], v[174:177], v[30:33]
	v_mfma_f32_16x16x32_f16 v[26:29], v[158:161], v[174:177], v[26:29]
	v_mfma_f32_16x16x32_f16 v[26:29], v[154:157], v[170:173], v[26:29]
	v_mfma_f32_16x16x32_f16 v[10:13], v[154:157], v[162:165], v[10:13]
	v_mfma_f32_16x16x32_f16 v[10:13], v[158:161], v[166:169], v[10:13]
	v_mfma_f32_16x16x32_f16 v[14:17], v[150:153], v[166:169], v[14:17]
	v_mfma_f32_16x16x32_f16 v[14:17], v[146:149], v[162:165], v[14:17]
	v_mfma_f32_16x16x32_f16 v[54:57], v[130:133], v[186:189], v[54:57]
	v_mfma_f32_16x16x32_f16 v[54:57], v[134:137], v[190:193], v[54:57]
	v_mfma_f32_16x16x32_f16 v[50:53], v[142:145], v[190:193], v[50:53]
	v_mfma_f32_16x16x32_f16 v[50:53], v[138:141], v[186:189], v[50:53]
	v_mfma_f32_16x16x32_f16 v[34:37], v[138:141], v[178:181], v[34:37]
	v_mfma_f32_16x16x32_f16 v[34:37], v[142:145], v[182:185], v[34:37]
	v_mfma_f32_16x16x32_f16 v[38:41], v[134:137], v[182:185], v[38:41]
	v_mfma_f32_16x16x32_f16 v[38:41], v[130:133], v[178:181], v[38:41]
	v_mfma_f32_16x16x32_f16 v[22:25], v[130:133], v[170:173], v[22:25]
	v_mfma_f32_16x16x32_f16 v[22:25], v[134:137], v[174:177], v[22:25]
	v_mfma_f32_16x16x32_f16 v[18:21], v[142:145], v[174:177], v[18:21]
	v_mfma_f32_16x16x32_f16 v[18:21], v[138:141], v[170:173], v[18:21]
	v_mfma_f32_16x16x32_f16 v[2:5], v[138:141], v[162:165], v[2:5]
	v_mfma_f32_16x16x32_f16 v[2:5], v[142:145], v[166:169], v[2:5]
	v_mfma_f32_16x16x32_f16 v[6:9], v[134:137], v[166:169], v[6:9]
	v_mfma_f32_16x16x32_f16 v[6:9], v[130:133], v[162:165], v[6:9]
	s_barrier
	s_setprio 0
	ds_read_b128 v[146:149], v204
	ds_read_b128 v[150:153], v204 offset:1024
	ds_read_b128 v[154:157], v204 offset:2048
	ds_read_b128 v[158:161], v204 offset:3072
	ds_read_b128 v[130:133], v205
	ds_read_b128 v[134:137], v205 offset:1024
	ds_read_b128 v[138:141], v205 offset:2048
	ds_read_b128 v[142:145], v205 offset:3072
	ds_read_b128 v[186:189], v203 offset:32768
	ds_read_b128 v[190:193], v203 offset:33792
	ds_read_b128 v[178:181], v203 offset:34816
	ds_read_b128 v[182:185], v203 offset:35840
	ds_read_b128 v[170:173], v203 offset:36864
	ds_read_b128 v[174:177], v203 offset:37888
	ds_read_b128 v[162:165], v203 offset:38912
	ds_read_b128 v[166:169], v203 offset:39936
	v_cndmask_b32_e64 v209, 0, 1, s[26:27]
	v_cmp_ne_u32_e64 s[6:7], 1, v209
	s_andn2_b64 vcc, exec, s[26:27]
	s_mov_b64 s[26:27], -1
	s_cbranch_vccnz .LBB0_1119
	s_add_u32 s26, s24, 0x40000
	s_addc_u32 s27, s25, 0
	s_add_u32 m0, s28, 0x4000
	s_nop 0
	global_load_lds_dwordx4 v1, s[26:27]
	s_nop 0
	s_add_u32 m0, s28, 0x6000
	s_nop 0
	global_load_lds_dwordx4 v199, s[26:27]
	s_waitcnt vmcnt(8)
	s_mov_b64 s[26:27], 0

; #define PG8_STAGE(bufoff, gbase, voff) do { if constexpr (ABL & 1) break; glds16s<(bufoff)>((voff)[0], (const void*)(gbase), ldsbw); glds16s<(bufoff) + 8192>((voff)[1], (const void*)(gbase), ldsbw); } while (0)
; #define PG8_LDA(dst, b, h) do { if constexpr (ABL & 4) break; _Pragma("unroll") for (int m = 0; m < 4; ++m) _Pragma("unroll") for (int k = 0; k < 2; ++k) dst[m][k] = *(const LAS f16x8*)(lds + PG8_SA(b, h) + aoff + m * 2048 + k * 1024); } while (0)
; #define PG8_MMA(ai, bj, At, Bt) do { if constexpr (ABL & 2) break; __builtin_amdgcn_s_setprio(1); _Pragma("unroll") for (int m = 0; m < 4; ++m) _Pragma("unroll") for (int n = 0; n < 2; ++n) _Pragma("unroll") for (int k = 0; k < 2; ++k) \
;         acc[ai][bj][m][n] = __builtin_amdgcn_mfma_f32_16x16x32_f16(Bt[n][k], At[m][k], acc[ai][bj][m][n], 0, 0, 0); __builtin_amdgcn_s_setprio(0); } while (0)
; #define PG8_WAIT_V(n) asm volatile("s_waitcnt vmcnt(" #n ")" ::: "memory")
; #define PG8_WAIT_L(n) asm volatile("s_waitcnt lgkmcnt(" #n ")" ::: "memory")
; #define PG8_BAR __builtin_amdgcn_s_barrier()
; #define PG8_SCHED __builtin_amdgcn_sched_barrier(0)
;     ...
;             if (!fin) PG8_WAIT_V(8); else PG8_WAIT_V(0); PG8_WAIT_L(0); PG8_BAR; PG8_MMA(0, 0, At, B0); PG8_MMA(0, 1, At, B1); PG8_BAR; PG8_SCHED;
;             PG8_LDA(At, 1, 1); if (!fin) { PG8_STAGE(PG8_SB(1, 0), b3, voffB); PG8_STAGE(PG8_SB(1, 1), b3 + hstep, voffB); PG8_STAGE(PG8_SA(1, 0), a3, voffA); }
;             if (!fin) PG8_WAIT_V(8); PG8_WAIT_L(0); PG8_BAR; PG8_MMA(1, 0, At, B0); PG8_MMA(1, 1, At, B1); PG8_BAR; PG8_SCHED;
.LBB0_1121:
	s_waitcnt lgkmcnt(0)
	s_barrier
	v_mfma_f32_16x16x32_f16 v[126:129], v[146:149], v[186:189], v[126:129]
	s_setprio 1
	v_mfma_f32_16x16x32_f16 v[126:129], v[150:153], v[190:193], v[126:129]
	v_mfma_f32_16x16x32_f16 v[122:125], v[158:161], v[190:193], v[122:125]
	v_mfma_f32_16x16x32_f16 v[122:125], v[154:157], v[186:189], v[122:125]
	v_mfma_f32_16x16x32_f16 v[106:109], v[154:157], v[178:181], v[106:109]
	v_mfma_f32_16x16x32_f16 v[106:109], v[158:161], v[182:185], v[106:109]
	v_mfma_f32_16x16x32_f16 v[110:113], v[150:153], v[182:185], v[110:113]
	v_mfma_f32_16x16x32_f16 v[110:113], v[146:149], v[178:181], v[110:113]
	v_mfma_f32_16x16x32_f16 v[94:97], v[146:149], v[170:173], v[94:97]
	v_mfma_f32_16x16x32_f16 v[94:97], v[150:153], v[174:177], v[94:97]
	v_mfma_f32_16x16x32_f16 v[90:93], v[158:161], v[174:177], v[90:93]
	v_mfma_f32_16x16x32_f16 v[90:93], v[154:157], v[170:173], v[90:93]
	v_mfma_f32_16x16x32_f16 v[74:77], v[154:157], v[162:165], v[74:77]
	v_mfma_f32_16x16x32_f16 v[74:77], v[158:161], v[166:169], v[74:77]
	v_mfma_f32_16x16x32_f16 v[78:81], v[150:153], v[166:169], v[78:81]
	v_mfma_f32_16x16x32_f16 v[78:81], v[146:149], v[162:165], v[78:81]
	v_mfma_f32_16x16x32_f16 v[118:121], v[130:133], v[186:189], v[118:121]
	v_mfma_f32_16x16x32_f16 v[118:121], v[134:137], v[190:193], v[118:121]
	v_mfma_f32_16x16x32_f16 v[114:117], v[142:145], v[190:193], v[114:117]
	v_mfma_f32_16x16x32_f16 v[114:117], v[138:141], v[186:189], v[114:117]
	v_mfma_f32_16x16x32_f16 v[98:101], v[138:141], v[178:181], v[98:101]
	v_mfma_f32_16x16x32_f16 v[98:101], v[142:145], v[182:185], v[98:101]
	v_mfma_f32_16x16x32_f16 v[102:105], v[134:137], v[182:185], v[102:105]
	v_mfma_f32_16x16x32_f16 v[102:105], v[130:133], v[178:181], v[102:105]
	v_mfma_f32_16x16x32_f16 v[86:89], v[130:133], v[170:173], v[86:89]
	v_mfma_f32_16x16x32_f16 v[86:89], v[134:137], v[174:177], v[86:89]
	v_mfma_f32_16x16x32_f16 v[82:85], v[142:145], v[174:177], v[82:85]
	v_mfma_f32_16x16x32_f16 v[82:85], v[138:141], v[170:173], v[82:85]
	v_mfma_f32_16x16x32_f16 v[66:69], v[138:141], v[162:165], v[66:69]
	v_mfma_f32_16x16x32_f16 v[66:69], v[142:145], v[166:169], v[66:69]
	v_mfma_f32_16x16x32_f16 v[70:73], v[134:137], v[166:169], v[70:73]
	v_mfma_f32_16x16x32_f16 v[70:73], v[130:133], v[162:165], v[70:73]
	s_barrier
	s_setprio 0
	ds_read_b128 v[186:189], v203 offset:49152
	ds_read_b128 v[190:193], v203 offset:50176
	ds_read_b128 v[178:181], v203 offset:51200
	ds_read_b128 v[182:185], v203 offset:52224
	ds_read_b128 v[170:173], v203 offset:53248
	ds_read_b128 v[174:177], v203 offset:54272
	ds_read_b128 v[162:165], v203 offset:55296
	ds_read_b128 v[166:169], v203 offset:56320
	s_and_b64 vcc, exec, s[6:7]
	s_cbranch_vccnz .LBB0_1112
	s_add_u32 s6, s24, 0x80
	s_addc_u32 s7, s25, 0
	s_add_u32 s24, s8, 0x80
	s_addc_u32 s25, s9, 0
	s_add_u32 m0, s28, 0x18000
	s_nop 0
	global_load_lds_dwordx4 v198, s[24:25]
	s_nop 0
	s_add_u32 m0, s28, 0x1a000
	s_nop 0
	global_load_lds_dwordx4 v200, s[24:25]
	s_add_u32 s8, s8, 0x40080
	s_addc_u32 s9, s9, 0
	s_add_u32 m0, s28, 0x1c000
	s_nop 0
	global_load_lds_dwordx4 v198, s[8:9]
	s_nop 0
	s_add_u32 m0, s28, 0x1e000
	s_nop 0
	global_load_lds_dwordx4 v200, s[8:9]
	s_nop 0
	s_add_u32 m0, s28, 0x8000
	s_nop 0
	global_load_lds_dwordx4 v1, s[6:7]
	s_nop 0
	s_add_u32 m0, s28, 0xa000
	s_nop 0
	global_load_lds_dwordx4 v199, s[6:7]
	s_waitcnt vmcnt(8)
	s_branch .LBB0_1112

; #define PG8_STAGE(bufoff, gbase, voff) do { if constexpr (ABL & 1) break; glds16s<(bufoff)>((voff)[0], (const void*)(gbase), ldsbw); glds16s<(bufoff) + 8192>((voff)[1], (const void*)(gbase), ldsbw); } while (0)
; #define PG8_LDA(dst, b, h) do { if constexpr (ABL & 4) break; _Pragma("unroll") for (int m = 0; m < 4; ++m) _Pragma("unroll") for (int k = 0; k < 2; ++k) dst[m][k] = *(const LAS f16x8*)(lds + PG8_SA(b, h) + aoff + m * 2048 + k * 1024); } while (0)
; #define PG8_LDB(dst, b, h) do { if constexpr (ABL & 4) break; _Pragma("unroll") for (int n = 0; n < 2; ++n) _Pragma("unroll") for (int k = 0; k < 2; ++k) dst[n][k] = *(const LAS f16x8*)(lds + PG8_SB(b, h) + boff + n * 2048 + k * 1024); } while (0)
; #define PG8_BAR __builtin_amdgcn_s_barrier()
;     ...
;         for (int t = 0; t < nt; t += 2) {
;             const bool last = (t == nt - 2);
;             const char* a1 = cA + (size_t)(t + 1) * kstep;
;             const char* a2 = last ? nA : cA + (size_t)(t + 2) * kstep; const char* b2 = last ? nB : cB + (size_t)(t + 2) * kstep;
;             const char* a3 = a2 + kstep; const char* b3 = b2 + kstep;
;             if (last && has_next) S.a_ready(nxt);
;             if constexpr (SP2) {
;             PG8_LDB(B0, 0, 0); PG8_LDB(B1, 0, 1); PG8_SCHED; PG8_LDA(At, 0, 0); PG8_STAGE(PG8_SA(1, 1), a1 + hstep, voffA);
;             PG8_WAIT_V(8); PG8_WAIT_L(0); PG8_BAR; PG8_MMAF(0, 0, At, B0); PG8_MMAF(0, 1, At, B1); PG8_BAR; PG8_SCHED;
;             const bool fin = last && !has_next;
;             PG8_LDA(At, 0, 1); if (!fin) { PG8_STAGE(PG8_SB(0, 0), b2, voffB); PG8_STAGE(PG8_SB(0, 1), b2 + hstep, voffB); PG8_STAGE(PG8_SA(0, 0), a2, voffA); }
;             if (!fin) PG8_WAIT_V(8); else PG8_WAIT_V(2); PG8_WAIT_L(0); PG8_BAR; PG8_MMAF(1, 0, At, B0); PG8_MMAF(1, 1, At, B1); PG8_BAR; PG8_SCHED;
;             PG8_LDB(B0, 1, 0); PG8_LDB(B1, 1, 1); PG8_SCHED; PG8_LDA(At, 1, 0); if (!fin) PG8_STAGE(PG8_SA(0, 1), a2 + hstep, voffA);
;             if (!fin) PG8_WAIT_V(8); else PG8_WAIT_V(0); PG8_WAIT_L(0); PG8_BAR; PG8_MMA(0, 0, At, B0); PG8_MMA(0, 1, At, B1); PG8_BAR; PG8_SCHED;
;             PG8_LDA(At, 1, 1); if (!fin) { PG8_STAGE(PG8_SB(1, 0), b3, voffB); PG8_STAGE(PG8_SB(1, 1), b3 + hstep, voffB); PG8_STAGE(PG8_SA(1, 0), a3, voffA); }
;             if (!fin) PG8_WAIT_V(8); PG8_WAIT_L(0); PG8_BAR; PG8_MMA(1, 0, At, B0); PG8_MMA(1, 1, At, B1); PG8_BAR; PG8_SCHED;
.LBB0_1164:
	s_waitcnt lgkmcnt(0)
	s_barrier
	v_mfma_f32_16x16x32_f16 v[62:65], v[158:161], v[186:189], v[62:65]
	s_setprio 1
	v_mfma_f32_16x16x32_f16 v[62:65], v[162:165], v[190:193], v[62:65]
	v_mfma_f32_16x16x32_f16 v[58:61], v[170:173], v[190:193], v[58:61]
	v_mfma_f32_16x16x32_f16 v[58:61], v[166:169], v[186:189], v[58:61]
	v_mfma_f32_16x16x32_f16 v[42:45], v[166:169], v[178:181], v[42:45]
	v_mfma_f32_16x16x32_f16 v[42:45], v[170:173], v[182:185], v[42:45]
	v_mfma_f32_16x16x32_f16 v[46:49], v[162:165], v[182:185], v[46:49]
	v_mfma_f32_16x16x32_f16 v[46:49], v[158:161], v[178:181], v[46:49]
	v_mfma_f32_16x16x32_f16 v[30:33], v[158:161], v[122:125], v[30:33]
	v_mfma_f32_16x16x32_f16 v[30:33], v[162:165], v[174:177], v[30:33]
	v_mfma_f32_16x16x32_f16 v[26:29], v[170:173], v[174:177], v[26:29]
	v_mfma_f32_16x16x32_f16 v[26:29], v[166:169], v[122:125], v[26:29]
	v_mfma_f32_16x16x32_f16 v[10:13], v[166:169], v[114:117], v[10:13]
	v_mfma_f32_16x16x32_f16 v[10:13], v[170:173], v[118:121], v[10:13]
	v_mfma_f32_16x16x32_f16 v[14:17], v[162:165], v[118:121], v[14:17]
	v_mfma_f32_16x16x32_f16 v[14:17], v[158:161], v[114:117], v[14:17]
	v_mfma_f32_16x16x32_f16 v[54:57], v[130:133], v[186:189], v[54:57]
	v_mfma_f32_16x16x32_f16 v[54:57], v[146:149], v[190:193], v[54:57]
	v_mfma_f32_16x16x32_f16 v[50:53], v[154:157], v[190:193], v[50:53]
	v_mfma_f32_16x16x32_f16 v[50:53], v[150:153], v[186:189], v[50:53]
	v_mfma_f32_16x16x32_f16 v[34:37], v[150:153], v[178:181], v[34:37]
	v_mfma_f32_16x16x32_f16 v[34:37], v[154:157], v[182:185], v[34:37]
	v_mfma_f32_16x16x32_f16 v[38:41], v[146:149], v[182:185], v[38:41]
	v_mfma_f32_16x16x32_f16 v[38:41], v[130:133], v[178:181], v[38:41]
	v_mfma_f32_16x16x32_f16 v[22:25], v[130:133], v[122:125], v[22:25]
	v_mfma_f32_16x16x32_f16 v[22:25], v[146:149], v[174:177], v[22:25]
	v_mfma_f32_16x16x32_f16 v[18:21], v[154:157], v[174:177], v[18:21]
	v_mfma_f32_16x16x32_f16 v[18:21], v[150:153], v[122:125], v[18:21]
	v_mfma_f32_16x16x32_f16 v[2:5], v[150:153], v[114:117], v[2:5]
	v_mfma_f32_16x16x32_f16 v[2:5], v[154:157], v[118:121], v[2:5]
	v_mfma_f32_16x16x32_f16 v[6:9], v[146:149], v[118:121], v[6:9]
	v_mfma_f32_16x16x32_f16 v[6:9], v[130:133], v[114:117], v[6:9]
	s_barrier
	s_setprio 0
	s_add_i32 s58, s58, 2
	s_add_u32 s54, s54, 0x100
	s_addc_u32 s55, s55, 0
	s_cmp_gt_u32 s58, 13
	s_cbranch_scc1 .LBB0_1175

; #define PG8_STAGE(bufoff, gbase, voff) do { if constexpr (ABL & 1) break; glds16s<(bufoff)>((voff)[0], (const void*)(gbase), ldsbw); glds16s<(bufoff) + 8192>((voff)[1], (const void*)(gbase), ldsbw); } while (0)
; #define PG8_LDA(dst, b, h) do { if constexpr (ABL & 4) break; _Pragma("unroll") for (int m = 0; m < 4; ++m) _Pragma("unroll") for (int k = 0; k < 2; ++k) dst[m][k] = *(const LAS f16x8*)(lds + PG8_SA(b, h) + aoff + m * 2048 + k * 1024); } while (0)
; #define PG8_LDB(dst, b, h) do { if constexpr (ABL & 4) break; _Pragma("unroll") for (int n = 0; n < 2; ++n) _Pragma("unroll") for (int k = 0; k < 2; ++k) dst[n][k] = *(const LAS f16x8*)(lds + PG8_SB(b, h) + boff + n * 2048 + k * 1024); } while (0)
; #define PG8_MMA(ai, bj, At, Bt) do { if constexpr (ABL & 2) break; __builtin_amdgcn_s_setprio(1); _Pragma("unroll") for (int m = 0; m < 4; ++m) _Pragma("unroll") for (int n = 0; n < 2; ++n) _Pragma("unroll") for (int k = 0; k < 2; ++k) \
;         acc[ai][bj][m][n] = __builtin_amdgcn_mfma_f32_16x16x32_f16(Bt[n][k], At[m][k], acc[ai][bj][m][n], 0, 0, 0); __builtin_amdgcn_s_setprio(0); } while (0)
; #define PG8_MMAF(ai, bj, At, Bt) do { if (t == 0) PG8_MMA0(ai, bj, At, Bt); else PG8_MMA(ai, bj, At, Bt); } while (0)
; #define PG8_WAIT_V(n) asm volatile("s_waitcnt vmcnt(" #n ")" ::: "memory")
; #define PG8_WAIT_L(n) asm volatile("s_waitcnt lgkmcnt(" #n ")" ::: "memory")
; #define PG8_BAR __builtin_amdgcn_s_barrier()
; #define PG8_SCHED __builtin_amdgcn_sched_barrier(0)
;     ...
;             if (!fin) PG8_WAIT_V(8); else PG8_WAIT_V(2); PG8_WAIT_L(0); PG8_BAR; PG8_MMAF(1, 0, At, B0); PG8_MMAF(1, 1, At, B1); PG8_BAR; PG8_SCHED;
;             PG8_LDB(B0, 1, 0); PG8_LDB(B1, 1, 1); PG8_SCHED; PG8_LDA(At, 1, 0); if (!fin) PG8_STAGE(PG8_SA(0, 1), a2 + hstep, voffA);
;             if (!fin) PG8_WAIT_V(8); else PG8_WAIT_V(0); PG8_WAIT_L(0); PG8_BAR; PG8_MMA(0, 0, At, B0); PG8_MMA(0, 1, At, B1); PG8_BAR; PG8_SCHED;
.LBB0_1169:
	s_waitcnt lgkmcnt(0)
	s_xor_b64 s[26:27], s[6:7], -1
	s_barrier
	v_mfma_f32_16x16x32_f16 v[62:65], v[158:161], v[186:189], v[62:65]
	s_setprio 1
	v_mfma_f32_16x16x32_f16 v[62:65], v[162:165], v[190:193], v[62:65]
	v_mfma_f32_16x16x32_f16 v[58:61], v[170:173], v[190:193], v[58:61]
	v_mfma_f32_16x16x32_f16 v[58:61], v[166:169], v[186:189], v[58:61]
	v_mfma_f32_16x16x32_f16 v[42:45], v[166:169], v[178:181], v[42:45]
	v_mfma_f32_16x16x32_f16 v[42:45], v[170:173], v[182:185], v[42:45]
	v_mfma_f32_16x16x32_f16 v[46:49], v[162:165], v[182:185], v[46:49]
	v_mfma_f32_16x16x32_f16 v[46:49], v[158:161], v[178:181], v[46:49]
	v_mfma_f32_16x16x32_f16 v[30:33], v[158:161], v[142:145], v[30:33]
	v_mfma_f32_16x16x32_f16 v[30:33], v[162:165], v[174:177], v[30:33]
	v_mfma_f32_16x16x32_f16 v[26:29], v[170:173], v[174:177], v[26:29]
	v_mfma_f32_16x16x32_f16 v[26:29], v[166:169], v[142:145], v[26:29]
	v_mfma_f32_16x16x32_f16 v[10:13], v[166:169], v[134:137], v[10:13]
	v_mfma_f32_16x16x32_f16 v[10:13], v[170:173], v[138:141], v[10:13]
	v_mfma_f32_16x16x32_f16 v[14:17], v[162:165], v[138:141], v[14:17]
	v_mfma_f32_16x16x32_f16 v[14:17], v[158:161], v[134:137], v[14:17]
	v_mfma_f32_16x16x32_f16 v[54:57], v[130:133], v[186:189], v[54:57]
	v_mfma_f32_16x16x32_f16 v[54:57], v[146:149], v[190:193], v[54:57]
	v_mfma_f32_16x16x32_f16 v[50:53], v[154:157], v[190:193], v[50:53]
	v_mfma_f32_16x16x32_f16 v[50:53], v[150:153], v[186:189], v[50:53]
	v_mfma_f32_16x16x32_f16 v[34:37], v[150:153], v[178:181], v[34:37]
	v_mfma_f32_16x16x32_f16 v[34:37], v[154:157], v[182:185], v[34:37]
	v_mfma_f32_16x16x32_f16 v[38:41], v[146:149], v[182:185], v[38:41]
	v_mfma_f32_16x16x32_f16 v[38:41], v[130:133], v[178:181], v[38:41]
	v_mfma_f32_16x16x32_f16 v[22:25], v[130:133], v[142:145], v[22:25]
	v_mfma_f32_16x16x32_f16 v[22:25], v[146:149], v[174:177], v[22:25]
	v_mfma_f32_16x16x32_f16 v[18:21], v[154:157], v[174:177], v[18:21]
	v_mfma_f32_16x16x32_f16 v[18:21], v[150:153], v[142:145], v[18:21]
	v_mfma_f32_16x16x32_f16 v[2:5], v[150:153], v[134:137], v[2:5]
	v_mfma_f32_16x16x32_f16 v[2:5], v[154:157], v[138:141], v[2:5]
	v_mfma_f32_16x16x32_f16 v[6:9], v[146:149], v[138:141], v[6:9]
	v_mfma_f32_16x16x32_f16 v[6:9], v[130:133], v[134:137], v[6:9]
	s_barrier
	s_setprio 0
	ds_read_b128 v[158:161], v216
	ds_read_b128 v[162:165], v216 offset:1024
	ds_read_b128 v[166:169], v216 offset:2048
	ds_read_b128 v[170:173], v216 offset:3072
	ds_read_b128 v[130:133], v217
	ds_read_b128 v[146:149], v217 offset:1024
	ds_read_b128 v[150:153], v217 offset:2048
	ds_read_b128 v[154:157], v217 offset:3072
	ds_read_b128 v[198:201], v215 offset:32768
	ds_read_b128 v[202:205], v215 offset:33792
	ds_read_b128 v[190:193], v215 offset:34816
	ds_read_b128 v[194:197], v215 offset:35840
	ds_read_b128 v[182:185], v215 offset:36864
	ds_read_b128 v[186:189], v215 offset:37888
	ds_read_b128 v[174:177], v215 offset:38912
	ds_read_b128 v[178:181], v215 offset:39936
	v_cndmask_b32_e64 v134, 0, 1, s[26:27]
	v_cmp_ne_u32_e64 s[6:7], 1, v134
	s_andn2_b64 vcc, exec, s[26:27]
	s_mov_b64 s[26:27], -1
	s_cbranch_vccnz .LBB0_1171
	s_add_u32 s26, s24, 0x40000
	s_addc_u32 s27, s25, 0
	s_add_u32 m0, s35, 0x4000
	s_nop 0
	global_load_lds_dwordx4 v1, s[26:27]
	s_nop 0
	s_add_u32 m0, s35, 0x6000
	s_nop 0
	global_load_lds_dwordx4 v211, s[26:27]
	s_waitcnt vmcnt(8)
	s_mov_b64 s[26:27], 0
